# last unit of each GEMM phase: dead cross-unit prefetch redirected to the just-loaded (L2-hot) last two K-tiles instead of the unit's long-evicted first tiles
# speedup vs baseline: 1.0082x; 1.0082x over previous
.LBB0_183:
	s_ashr_i32 s13, s12, 31
	s_lshl_b64 s[24:25], s[12:13], 19
	s_add_u32 s24, s80, s24
	s_addc_u32 s25, s81, s25
	s_and_b64 s[30:31], s[4:5], exec
	s_cselect_b32 s13, s25, s45
	s_cselect_b32 s66, s24, s44
	s_ashr_i32 s11, s10, 31
	s_lshl_b64 s[30:31], s[10:11], 19
	s_add_u32 s30, s52, s30
	s_addc_u32 s31, s53, s31
	s_and_b64 s[48:49], s[4:5], exec
	s_cselect_b32 s11, s31, s47
	s_cselect_b32 s67, s30, s46
	s_cbranch_scc1 .Lnx_0
	s_add_u32 s66, s66, 0x700
	s_addc_u32 s13, s13, 0
	s_add_u32 s67, s67, 0x700
	s_addc_u32 s11, s11, 0
.Lnx_0:
	s_add_u32 s44, s44, 0x40080
	s_addc_u32 s45, s45, 0
	s_add_u32 s68, s46, 0x100
	s_addc_u32 s69, s47, 0
	s_mov_b32 s70, -2
	ds_read_b128 v[140:143], v147
	ds_read_b128 v[150:153], v147 offset:1024
	ds_read_b128 v[154:157], v147 offset:2048
	ds_read_b128 v[158:161], v147 offset:3072
	ds_read_b128 v[162:165], v148
	ds_read_b128 v[166:169], v148 offset:1024
	ds_read_b128 v[170:173], v148 offset:2048
	ds_read_b128 v[174:177], v148 offset:3072
	s_add_u32 s18, s44, 0xfffc0080
	s_addc_u32 s19, s45, -1
	s_cmp_eq_u32 s70, 12
	s_cselect_b32 s49, s13, s19
	s_cselect_b32 s48, s66, s18
	s_cselect_b32 s47, s11, s69
	s_cselect_b32 s46, s67, s68
	v_lshl_add_u64 v[178:179], s[44:45], 0, v[132:133]
	s_add_i32 m0, s37, 0xc000
	ds_read_b128 v[184:187], v149
	ds_read_b128 v[188:191], v149 offset:1024
	ds_read_b128 v[192:195], v149 offset:2048
	ds_read_b128 v[196:199], v149 offset:3072
	ds_read_b128 v[200:203], v149 offset:4096
	ds_read_b128 v[204:207], v149 offset:5120
	ds_read_b128 v[208:211], v149 offset:6144
	ds_read_b128 v[212:215], v149 offset:7168
	global_load_lds_dwordx4 v[178:179], off
	v_lshl_add_u64 v[178:179], s[44:45], 0, v[134:135]
	s_add_i32 m0, s37, 0xe000
	s_nop 0
	global_load_lds_dwordx4 v[178:179], off
	s_waitcnt vmcnt(8)
	s_waitcnt lgkmcnt(0)
	s_barrier
	s_setprio 1
	s_waitcnt lgkmcnt(0)
	v_mfma_f32_16x16x32_bf16 v[124:127], v[140:143], v[184:187], 0
	v_mfma_f32_16x16x32_bf16 v[124:127], v[150:153], v[188:191], v[124:127]
	v_mfma_f32_16x16x32_bf16 v[120:123], v[154:157], v[184:187], 0
	v_mfma_f32_16x16x32_bf16 v[120:123], v[158:161], v[188:191], v[120:123]
	v_mfma_f32_16x16x32_bf16 v[108:111], v[140:143], v[192:195], 0
	v_mfma_f32_16x16x32_bf16 v[108:111], v[150:153], v[196:199], v[108:111]
	v_mfma_f32_16x16x32_bf16 v[104:107], v[154:157], v[192:195], 0
	v_mfma_f32_16x16x32_bf16 v[104:107], v[158:161], v[196:199], v[104:107]
	v_mfma_f32_16x16x32_bf16 v[92:95], v[140:143], v[200:203], 0
	v_mfma_f32_16x16x32_bf16 v[92:95], v[150:153], v[204:207], v[92:95]
	v_mfma_f32_16x16x32_bf16 v[88:91], v[154:157], v[200:203], 0
	v_mfma_f32_16x16x32_bf16 v[88:91], v[158:161], v[204:207], v[88:91]
	v_mfma_f32_16x16x32_bf16 v[76:79], v[140:143], v[208:211], 0
	v_mfma_f32_16x16x32_bf16 v[76:79], v[150:153], v[212:215], v[76:79]
	v_mfma_f32_16x16x32_bf16 v[72:75], v[154:157], v[208:211], 0
	v_mfma_f32_16x16x32_bf16 v[72:75], v[158:161], v[212:215], v[72:75]
	v_mfma_f32_16x16x32_bf16 v[116:119], v[162:165], v[184:187], 0
	v_mfma_f32_16x16x32_bf16 v[116:119], v[166:169], v[188:191], v[116:119]
	v_mfma_f32_16x16x32_bf16 v[112:115], v[170:173], v[184:187], 0
	v_mfma_f32_16x16x32_bf16 v[112:115], v[174:177], v[188:191], v[112:115]
	v_mfma_f32_16x16x32_bf16 v[100:103], v[162:165], v[192:195], 0
	v_mfma_f32_16x16x32_bf16 v[100:103], v[166:169], v[196:199], v[100:103]
	v_mfma_f32_16x16x32_bf16 v[96:99], v[170:173], v[192:195], 0
	v_mfma_f32_16x16x32_bf16 v[96:99], v[174:177], v[196:199], v[96:99]
	v_mfma_f32_16x16x32_bf16 v[84:87], v[162:165], v[200:203], 0
	v_mfma_f32_16x16x32_bf16 v[84:87], v[166:169], v[204:207], v[84:87]
	v_mfma_f32_16x16x32_bf16 v[80:83], v[170:173], v[200:203], 0
	v_mfma_f32_16x16x32_bf16 v[80:83], v[174:177], v[204:207], v[80:83]
	v_mfma_f32_16x16x32_bf16 v[68:71], v[162:165], v[208:211], 0
	v_mfma_f32_16x16x32_bf16 v[68:71], v[166:169], v[212:215], v[68:71]
	v_mfma_f32_16x16x32_bf16 v[64:67], v[170:173], v[208:211], 0
	v_mfma_f32_16x16x32_bf16 v[64:67], v[174:177], v[212:215], v[64:67]
	s_setprio 0
	s_barrier
	s_add_i32 s18, s62, s54
	v_lshl_add_u64 v[178:179], s[46:47], 0, v[130:131]
	s_mov_b32 m0, s18
	ds_read_b128 v[184:187], v149 offset:16384
	ds_read_b128 v[188:191], v149 offset:17408
	ds_read_b128 v[192:195], v149 offset:18432
	ds_read_b128 v[196:199], v149 offset:19456
	ds_read_b128 v[200:203], v149 offset:20480
	ds_read_b128 v[204:207], v149 offset:21504
	ds_read_b128 v[208:211], v149 offset:22528
	ds_read_b128 v[212:215], v149 offset:23552
	global_load_lds_dwordx4 v[178:179], off
	s_add_i32 m0, s18, 0x2000
	s_add_u32 s72, s46, 0x40000
	v_lshl_add_u64 v[216:217], s[46:47], 0, v[128:129]
	s_addc_u32 s73, s47, 0
	s_add_i32 s18, s63, s54
	global_load_lds_dwordx4 v[216:217], off
	v_lshl_add_u64 v[218:219], s[72:73], 0, v[130:131]
	s_mov_b32 m0, s18
	v_lshl_add_u64 v[220:221], s[48:49], 0, v[128:129]
	global_load_lds_dwordx4 v[218:219], off
	v_lshl_add_u64 v[218:219], s[72:73], 0, v[128:129]
	s_add_i32 m0, s18, 0x2000
	s_nop 0
	global_load_lds_dwordx4 v[218:219], off
	v_lshl_add_u64 v[218:219], s[48:49], 0, v[130:131]
	s_mov_b32 m0, s37
	s_nop 0
	global_load_lds_dwordx4 v[218:219], off
	s_mov_b32 m0, s56
	s_nop 0
	global_load_lds_dwordx4 v[220:221], off
	s_waitcnt vmcnt(8)
	s_waitcnt lgkmcnt(0)
	s_barrier
	s_setprio 1
	s_waitcnt lgkmcnt(0)
	v_mfma_f32_16x16x32_bf16 v[60:63], v[140:143], v[184:187], 0
	v_mfma_f32_16x16x32_bf16 v[60:63], v[150:153], v[188:191], v[60:63]
	v_mfma_f32_16x16x32_bf16 v[56:59], v[154:157], v[184:187], 0
	v_mfma_f32_16x16x32_bf16 v[56:59], v[158:161], v[188:191], v[56:59]
	v_mfma_f32_16x16x32_bf16 v[44:47], v[140:143], v[192:195], 0
	v_mfma_f32_16x16x32_bf16 v[44:47], v[150:153], v[196:199], v[44:47]
	v_mfma_f32_16x16x32_bf16 v[40:43], v[154:157], v[192:195], 0
	v_mfma_f32_16x16x32_bf16 v[40:43], v[158:161], v[196:199], v[40:43]
	v_mfma_f32_16x16x32_bf16 v[28:31], v[140:143], v[200:203], 0
	v_mfma_f32_16x16x32_bf16 v[28:31], v[150:153], v[204:207], v[28:31]
	v_mfma_f32_16x16x32_bf16 v[24:27], v[154:157], v[200:203], 0
	v_mfma_f32_16x16x32_bf16 v[24:27], v[158:161], v[204:207], v[24:27]
	v_mfma_f32_16x16x32_bf16 v[12:15], v[140:143], v[208:211], 0
	v_mfma_f32_16x16x32_bf16 v[12:15], v[150:153], v[212:215], v[12:15]
	v_mfma_f32_16x16x32_bf16 v[8:11], v[154:157], v[208:211], 0
	v_mfma_f32_16x16x32_bf16 v[8:11], v[158:161], v[212:215], v[8:11]
	v_mfma_f32_16x16x32_bf16 v[52:55], v[162:165], v[184:187], 0
	v_mfma_f32_16x16x32_bf16 v[52:55], v[166:169], v[188:191], v[52:55]
	v_mfma_f32_16x16x32_bf16 v[48:51], v[170:173], v[184:187], 0
	v_mfma_f32_16x16x32_bf16 v[48:51], v[174:177], v[188:191], v[48:51]
	v_mfma_f32_16x16x32_bf16 v[36:39], v[162:165], v[192:195], 0
	v_mfma_f32_16x16x32_bf16 v[36:39], v[166:169], v[196:199], v[36:39]
	v_mfma_f32_16x16x32_bf16 v[32:35], v[170:173], v[192:195], 0
	v_mfma_f32_16x16x32_bf16 v[32:35], v[174:177], v[196:199], v[32:35]
	v_mfma_f32_16x16x32_bf16 v[20:23], v[162:165], v[200:203], 0
	v_mfma_f32_16x16x32_bf16 v[20:23], v[166:169], v[204:207], v[20:23]
	v_mfma_f32_16x16x32_bf16 v[16:19], v[170:173], v[200:203], 0
	v_mfma_f32_16x16x32_bf16 v[16:19], v[174:177], v[204:207], v[16:19]
	v_mfma_f32_16x16x32_bf16 v[4:7], v[162:165], v[208:211], 0
	v_mfma_f32_16x16x32_bf16 v[4:7], v[166:169], v[212:215], v[4:7]
	v_mfma_f32_16x16x32_bf16 v[0:3], v[170:173], v[208:211], 0
	v_mfma_f32_16x16x32_bf16 v[0:3], v[174:177], v[212:215], v[0:3]
	s_setprio 0
	s_barrier
	s_branch .Lmid_gemm0

.LBB0_263:
	s_cbranch_vccz .Lnx_1
	s_add_u32 s6, s6, 0x1500
	s_addc_u32 s7, s7, 0
	s_add_u32 s48, s48, 0x1500
	s_addc_u32 s49, s49, 0

.LBB0_386:
	s_ashr_i32 s49, s48, 31
	s_lshl_b64 s[52:53], s[48:49], 19
	s_add_u32 s52, s80, s52
	s_addc_u32 s53, s81, s53
	s_and_b64 s[54:55], s[4:5], exec
	s_cselect_b32 s49, s53, s59
	s_cselect_b32 s82, s52, s58
	s_ashr_i32 s47, s46, 31
	s_lshl_b64 s[54:55], s[46:47], 19
	s_add_u32 s54, s64, s54
	s_addc_u32 s55, s65, s55
	s_and_b64 s[62:63], s[4:5], exec
	s_cselect_b32 s47, s55, s61
	s_cselect_b32 s83, s54, s60
	s_cbranch_scc1 .Lnx_2
	s_add_u32 s82, s82, 0x700
	s_addc_u32 s49, s49, 0
	s_add_u32 s83, s83, 0x700
	s_addc_u32 s47, s47, 0
.Lnx_2:
	s_add_u32 s58, s58, 0x40080
	s_addc_u32 s59, s59, 0
	s_add_u32 s84, s60, 0x100
	s_addc_u32 s85, s61, 0
	s_mov_b32 s86, -2
	ds_read_b128 v[152:155], v148
	ds_read_b128 v[156:159], v148 offset:1024
	ds_read_b128 v[160:163], v148 offset:2048
	ds_read_b128 v[164:167], v148 offset:3072
	ds_read_b128 v[168:171], v149
	ds_read_b128 v[172:175], v149 offset:1024
	ds_read_b128 v[176:179], v149 offset:2048
	ds_read_b128 v[184:187], v149 offset:3072
	s_add_u32 s18, s58, 0xfffc0080
	s_addc_u32 s19, s59, -1
	s_cmp_eq_u32 s86, 12
	s_cselect_b32 s63, s49, s19
	s_cselect_b32 s62, s82, s18
	s_cselect_b32 s61, s47, s85
	s_cselect_b32 s60, s83, s84
	v_lshl_add_u64 v[220:221], s[58:59], 0, v[138:139]
	s_add_i32 m0, s68, 0xc000
	ds_read_b128 v[188:191], v150
	ds_read_b128 v[192:195], v150 offset:1024
	ds_read_b128 v[196:199], v150 offset:2048
	ds_read_b128 v[200:203], v150 offset:3072
	ds_read_b128 v[204:207], v150 offset:4096
	ds_read_b128 v[208:211], v150 offset:5120
	ds_read_b128 v[212:215], v150 offset:6144
	ds_read_b128 v[216:219], v150 offset:7168
	global_load_lds_dwordx4 v[220:221], off
	v_lshl_add_u64 v[220:221], s[58:59], 0, v[140:141]
	s_add_i32 m0, s68, 0xe000
	s_nop 0
	global_load_lds_dwordx4 v[220:221], off
	s_waitcnt vmcnt(8)
	s_waitcnt lgkmcnt(0)
	s_barrier
	s_setprio 1
	s_waitcnt lgkmcnt(0)
	v_mfma_f32_16x16x32_bf16 v[124:127], v[152:155], v[188:191], 0
	v_mfma_f32_16x16x32_bf16 v[124:127], v[156:159], v[192:195], v[124:127]
	v_mfma_f32_16x16x32_bf16 v[120:123], v[160:163], v[188:191], 0
	v_mfma_f32_16x16x32_bf16 v[120:123], v[164:167], v[192:195], v[120:123]
	v_mfma_f32_16x16x32_bf16 v[116:119], v[152:155], v[196:199], 0
	v_mfma_f32_16x16x32_bf16 v[116:119], v[156:159], v[200:203], v[116:119]
	v_mfma_f32_16x16x32_bf16 v[112:115], v[160:163], v[196:199], 0
	v_mfma_f32_16x16x32_bf16 v[112:115], v[164:167], v[200:203], v[112:115]
	v_mfma_f32_16x16x32_bf16 v[108:111], v[152:155], v[204:207], 0
	v_mfma_f32_16x16x32_bf16 v[108:111], v[156:159], v[208:211], v[108:111]
	v_mfma_f32_16x16x32_bf16 v[104:107], v[160:163], v[204:207], 0
	v_mfma_f32_16x16x32_bf16 v[104:107], v[164:167], v[208:211], v[104:107]
	v_mfma_f32_16x16x32_bf16 v[100:103], v[152:155], v[212:215], 0
	v_mfma_f32_16x16x32_bf16 v[100:103], v[156:159], v[216:219], v[100:103]
	v_mfma_f32_16x16x32_bf16 v[96:99], v[160:163], v[212:215], 0
	v_mfma_f32_16x16x32_bf16 v[96:99], v[164:167], v[216:219], v[96:99]
	v_mfma_f32_16x16x32_bf16 v[68:71], v[168:171], v[188:191], 0
	v_mfma_f32_16x16x32_bf16 v[68:71], v[172:175], v[192:195], v[68:71]
	v_mfma_f32_16x16x32_bf16 v[64:67], v[176:179], v[188:191], 0
	v_mfma_f32_16x16x32_bf16 v[64:67], v[184:187], v[192:195], v[64:67]
	v_mfma_f32_16x16x32_bf16 v[52:55], v[168:171], v[196:199], 0
	v_mfma_f32_16x16x32_bf16 v[52:55], v[172:175], v[200:203], v[52:55]
	v_mfma_f32_16x16x32_bf16 v[48:51], v[176:179], v[196:199], 0
	v_mfma_f32_16x16x32_bf16 v[48:51], v[184:187], v[200:203], v[48:51]
	v_mfma_f32_16x16x32_bf16 v[44:47], v[168:171], v[204:207], 0
	v_mfma_f32_16x16x32_bf16 v[44:47], v[172:175], v[208:211], v[44:47]
	v_mfma_f32_16x16x32_bf16 v[40:43], v[176:179], v[204:207], 0
	v_mfma_f32_16x16x32_bf16 v[40:43], v[184:187], v[208:211], v[40:43]
	v_mfma_f32_16x16x32_bf16 v[36:39], v[168:171], v[212:215], 0
	v_mfma_f32_16x16x32_bf16 v[36:39], v[172:175], v[216:219], v[36:39]
	v_mfma_f32_16x16x32_bf16 v[32:35], v[176:179], v[212:215], 0
	v_mfma_f32_16x16x32_bf16 v[32:35], v[184:187], v[216:219], v[32:35]
	s_setprio 0
	s_barrier
	s_add_i32 s18, s76, s66
	v_lshl_add_u64 v[220:221], s[60:61], 0, v[132:133]
	s_mov_b32 m0, s18
	ds_read_b128 v[188:191], v150 offset:16384
	ds_read_b128 v[192:195], v150 offset:17408
	ds_read_b128 v[196:199], v150 offset:18432
	ds_read_b128 v[200:203], v150 offset:19456
	ds_read_b128 v[204:207], v150 offset:20480
	ds_read_b128 v[208:211], v150 offset:21504
	ds_read_b128 v[212:215], v150 offset:22528
	ds_read_b128 v[216:219], v150 offset:23552
	global_load_lds_dwordx4 v[220:221], off
	s_add_i32 m0, s18, 0x2000
	s_add_u32 s88, s60, 0x40000
	v_lshl_add_u64 v[222:223], s[60:61], 0, v[128:129]
	s_addc_u32 s89, s61, 0
	s_add_i32 s18, s77, s66
	global_load_lds_dwordx4 v[222:223], off
	v_lshl_add_u64 v[224:225], s[88:89], 0, v[132:133]
	s_mov_b32 m0, s18
	v_lshl_add_u64 v[226:227], s[62:63], 0, v[130:131]
	global_load_lds_dwordx4 v[224:225], off
	v_lshl_add_u64 v[224:225], s[88:89], 0, v[128:129]
	s_add_i32 m0, s18, 0x2000
	s_nop 0
	global_load_lds_dwordx4 v[224:225], off
	v_lshl_add_u64 v[224:225], s[62:63], 0, v[134:135]
	s_mov_b32 m0, s68
	s_nop 0
	global_load_lds_dwordx4 v[224:225], off
	s_mov_b32 m0, s69
	s_nop 0
	global_load_lds_dwordx4 v[226:227], off
	s_waitcnt vmcnt(8)
	s_waitcnt lgkmcnt(0)
	s_barrier
	s_setprio 1
	s_waitcnt lgkmcnt(0)
	v_mfma_f32_16x16x32_bf16 v[92:95], v[152:155], v[188:191], 0
	v_mfma_f32_16x16x32_bf16 v[92:95], v[156:159], v[192:195], v[92:95]
	v_mfma_f32_16x16x32_bf16 v[88:91], v[160:163], v[188:191], 0
	v_mfma_f32_16x16x32_bf16 v[88:91], v[164:167], v[192:195], v[88:91]
	v_mfma_f32_16x16x32_bf16 v[84:87], v[152:155], v[196:199], 0
	v_mfma_f32_16x16x32_bf16 v[84:87], v[156:159], v[200:203], v[84:87]
	v_mfma_f32_16x16x32_bf16 v[80:83], v[160:163], v[196:199], 0
	v_mfma_f32_16x16x32_bf16 v[80:83], v[164:167], v[200:203], v[80:83]
	v_mfma_f32_16x16x32_bf16 v[76:79], v[152:155], v[204:207], 0
	v_mfma_f32_16x16x32_bf16 v[76:79], v[156:159], v[208:211], v[76:79]
	v_mfma_f32_16x16x32_bf16 v[72:75], v[160:163], v[204:207], 0
	v_mfma_f32_16x16x32_bf16 v[72:75], v[164:167], v[208:211], v[72:75]
	v_mfma_f32_16x16x32_bf16 v[60:63], v[152:155], v[212:215], 0
	v_mfma_f32_16x16x32_bf16 v[60:63], v[156:159], v[216:219], v[60:63]
	v_mfma_f32_16x16x32_bf16 v[56:59], v[160:163], v[212:215], 0
	v_mfma_f32_16x16x32_bf16 v[56:59], v[164:167], v[216:219], v[56:59]
	v_mfma_f32_16x16x32_bf16 v[28:31], v[168:171], v[188:191], 0
	v_mfma_f32_16x16x32_bf16 v[28:31], v[172:175], v[192:195], v[28:31]
	v_mfma_f32_16x16x32_bf16 v[24:27], v[176:179], v[188:191], 0
	v_mfma_f32_16x16x32_bf16 v[24:27], v[184:187], v[192:195], v[24:27]
	v_mfma_f32_16x16x32_bf16 v[20:23], v[168:171], v[196:199], 0
	v_mfma_f32_16x16x32_bf16 v[20:23], v[172:175], v[200:203], v[20:23]
	v_mfma_f32_16x16x32_bf16 v[16:19], v[176:179], v[196:199], 0
	v_mfma_f32_16x16x32_bf16 v[16:19], v[184:187], v[200:203], v[16:19]
	v_mfma_f32_16x16x32_bf16 v[12:15], v[168:171], v[204:207], 0
	v_mfma_f32_16x16x32_bf16 v[12:15], v[172:175], v[208:211], v[12:15]
	v_mfma_f32_16x16x32_bf16 v[8:11], v[176:179], v[204:207], 0
	v_mfma_f32_16x16x32_bf16 v[8:11], v[184:187], v[208:211], v[8:11]
	v_mfma_f32_16x16x32_bf16 v[4:7], v[168:171], v[212:215], 0
	v_mfma_f32_16x16x32_bf16 v[4:7], v[172:175], v[216:219], v[4:7]
	v_mfma_f32_16x16x32_bf16 v[0:3], v[176:179], v[212:215], 0
	v_mfma_f32_16x16x32_bf16 v[0:3], v[184:187], v[216:219], v[0:3]
	s_setprio 0
	s_barrier
	s_branch .Lmid_gemm2

.LBB0_600:
	s_ashr_i32 s49, s48, 31
	s_lshl_b64 s[18:19], s[48:49], 19
	s_add_u32 s52, s38, s18
	s_addc_u32 s53, s39, s19
	s_and_b64 s[18:19], s[4:5], exec
	s_cselect_b32 s49, s53, s59
	s_cselect_b32 s84, s52, s58
	s_ashr_i32 s47, s46, 31
	s_lshl_b64 s[18:19], s[46:47], 19
	s_add_u32 s54, s64, s18
	s_addc_u32 s55, s65, s19
	s_and_b64 s[18:19], s[4:5], exec
	s_cselect_b32 s47, s55, s61
	s_cselect_b32 s85, s54, s60
	s_cbranch_scc1 .Lnx_3
	s_add_u32 s84, s84, 0x700
	s_addc_u32 s49, s49, 0
	s_add_u32 s85, s85, 0x700
	s_addc_u32 s47, s47, 0
.Lnx_3:
	s_add_u32 s58, s58, 0x40080
	s_addc_u32 s59, s59, 0
	s_add_u32 s86, s60, 0x100
	s_addc_u32 s87, s61, 0
	s_mov_b32 s88, -2
	ds_read_b128 v[152:155], v149
	ds_read_b128 v[156:159], v149 offset:1024
	ds_read_b128 v[160:163], v149 offset:2048
	ds_read_b128 v[164:167], v149 offset:3072
	ds_read_b128 v[168:171], v150
	ds_read_b128 v[172:175], v150 offset:1024
	ds_read_b128 v[176:179], v150 offset:2048
	ds_read_b128 v[184:187], v150 offset:3072
	s_add_u32 s18, s58, 0xfffc0080
	s_addc_u32 s19, s59, -1
	s_cmp_eq_u32 s88, 12
	s_cselect_b32 s63, s49, s19
	s_cselect_b32 s62, s84, s18
	s_cselect_b32 s61, s47, s87
	s_cselect_b32 s60, s85, s86
	v_lshl_add_u64 v[144:145], s[58:59], 0, v[136:137]
	s_add_i32 m0, s57, 0xc000
	ds_read_b128 v[188:191], v151
	ds_read_b128 v[192:195], v151 offset:1024
	ds_read_b128 v[196:199], v151 offset:2048
	ds_read_b128 v[200:203], v151 offset:3072
	ds_read_b128 v[204:207], v151 offset:4096
	ds_read_b128 v[208:211], v151 offset:5120
	ds_read_b128 v[212:215], v151 offset:6144
	ds_read_b128 v[216:219], v151 offset:7168
	global_load_lds_dwordx4 v[144:145], off
	v_lshl_add_u64 v[144:145], s[58:59], 0, v[138:139]
	s_add_i32 m0, s57, 0xe000
	s_nop 0
	global_load_lds_dwordx4 v[144:145], off
	s_waitcnt vmcnt(8)
	s_waitcnt lgkmcnt(0)
	s_barrier
	s_setprio 1
	s_waitcnt lgkmcnt(0)
	v_mfma_f32_16x16x32_bf16 v[124:127], v[152:155], v[188:191], 0
	v_mfma_f32_16x16x32_bf16 v[124:127], v[156:159], v[192:195], v[124:127]
	v_mfma_f32_16x16x32_bf16 v[120:123], v[160:163], v[188:191], 0
	v_mfma_f32_16x16x32_bf16 v[120:123], v[164:167], v[192:195], v[120:123]
	v_mfma_f32_16x16x32_bf16 v[116:119], v[152:155], v[196:199], 0
	v_mfma_f32_16x16x32_bf16 v[116:119], v[156:159], v[200:203], v[116:119]
	v_mfma_f32_16x16x32_bf16 v[108:111], v[160:163], v[196:199], 0
	v_mfma_f32_16x16x32_bf16 v[108:111], v[164:167], v[200:203], v[108:111]
	v_mfma_f32_16x16x32_bf16 v[100:103], v[152:155], v[204:207], 0
	v_mfma_f32_16x16x32_bf16 v[100:103], v[156:159], v[208:211], v[100:103]
	v_mfma_f32_16x16x32_bf16 v[92:95], v[160:163], v[204:207], 0
	v_mfma_f32_16x16x32_bf16 v[92:95], v[164:167], v[208:211], v[92:95]
	v_mfma_f32_16x16x32_bf16 v[84:87], v[152:155], v[212:215], 0
	v_mfma_f32_16x16x32_bf16 v[84:87], v[156:159], v[216:219], v[84:87]
	v_mfma_f32_16x16x32_bf16 v[76:79], v[160:163], v[212:215], 0
	v_mfma_f32_16x16x32_bf16 v[76:79], v[164:167], v[216:219], v[76:79]
	v_mfma_f32_16x16x32_bf16 v[112:115], v[168:171], v[188:191], 0
	v_mfma_f32_16x16x32_bf16 v[112:115], v[172:175], v[192:195], v[112:115]
	v_mfma_f32_16x16x32_bf16 v[104:107], v[176:179], v[188:191], 0
	v_mfma_f32_16x16x32_bf16 v[104:107], v[184:187], v[192:195], v[104:107]
	v_mfma_f32_16x16x32_bf16 v[96:99], v[168:171], v[196:199], 0
	v_mfma_f32_16x16x32_bf16 v[96:99], v[172:175], v[200:203], v[96:99]
	v_mfma_f32_16x16x32_bf16 v[88:91], v[176:179], v[196:199], 0
	v_mfma_f32_16x16x32_bf16 v[88:91], v[184:187], v[200:203], v[88:91]
	v_mfma_f32_16x16x32_bf16 v[80:83], v[168:171], v[204:207], 0
	v_mfma_f32_16x16x32_bf16 v[80:83], v[172:175], v[208:211], v[80:83]
	v_mfma_f32_16x16x32_bf16 v[72:75], v[176:179], v[204:207], 0
	v_mfma_f32_16x16x32_bf16 v[72:75], v[184:187], v[208:211], v[72:75]
	v_mfma_f32_16x16x32_bf16 v[68:71], v[168:171], v[212:215], 0
	v_mfma_f32_16x16x32_bf16 v[68:71], v[172:175], v[216:219], v[68:71]
	v_mfma_f32_16x16x32_bf16 v[64:67], v[176:179], v[212:215], 0
	v_mfma_f32_16x16x32_bf16 v[64:67], v[184:187], v[216:219], v[64:67]
	s_setprio 0
	s_barrier
	s_add_i32 s18, s73, s66
	v_lshl_add_u64 v[144:145], s[60:61], 0, v[130:131]
	s_mov_b32 m0, s18
	ds_read_b128 v[188:191], v151 offset:16384
	ds_read_b128 v[192:195], v151 offset:17408
	ds_read_b128 v[196:199], v151 offset:18432
	ds_read_b128 v[200:203], v151 offset:19456
	ds_read_b128 v[204:207], v151 offset:20480
	ds_read_b128 v[208:211], v151 offset:21504
	ds_read_b128 v[212:215], v151 offset:22528
	ds_read_b128 v[216:219], v151 offset:23552
	global_load_lds_dwordx4 v[144:145], off
	s_add_i32 m0, s18, 0x2000
	s_add_u32 s18, s60, 0x40000
	v_lshl_add_u64 v[220:221], s[60:61], 0, v[134:135]
	s_addc_u32 s19, s61, 0
	s_add_i32 s79, s74, s66
	global_load_lds_dwordx4 v[220:221], off
	v_lshl_add_u64 v[222:223], s[18:19], 0, v[130:131]
	s_mov_b32 m0, s79
	v_lshl_add_u64 v[224:225], s[62:63], 0, v[132:133]
	global_load_lds_dwordx4 v[222:223], off
	v_lshl_add_u64 v[222:223], s[18:19], 0, v[134:135]
	s_add_i32 m0, s79, 0x2000
	s_nop 0
	global_load_lds_dwordx4 v[222:223], off
	v_lshl_add_u64 v[222:223], s[62:63], 0, v[128:129]
	s_mov_b32 m0, s57
	s_nop 0
	global_load_lds_dwordx4 v[222:223], off
	s_mov_b32 m0, s67
	s_nop 0
	global_load_lds_dwordx4 v[224:225], off
	s_waitcnt vmcnt(8)
	s_waitcnt lgkmcnt(0)
	s_barrier
	s_setprio 1
	s_waitcnt lgkmcnt(0)
	v_mfma_f32_16x16x32_bf16 v[60:63], v[152:155], v[188:191], 0
	v_mfma_f32_16x16x32_bf16 v[60:63], v[156:159], v[192:195], v[60:63]
	v_mfma_f32_16x16x32_bf16 v[56:59], v[160:163], v[188:191], 0
	v_mfma_f32_16x16x32_bf16 v[56:59], v[164:167], v[192:195], v[56:59]
	v_mfma_f32_16x16x32_bf16 v[52:55], v[152:155], v[196:199], 0
	v_mfma_f32_16x16x32_bf16 v[52:55], v[156:159], v[200:203], v[52:55]
	v_mfma_f32_16x16x32_bf16 v[44:47], v[160:163], v[196:199], 0
	v_mfma_f32_16x16x32_bf16 v[44:47], v[164:167], v[200:203], v[44:47]
	v_mfma_f32_16x16x32_bf16 v[36:39], v[152:155], v[204:207], 0
	v_mfma_f32_16x16x32_bf16 v[36:39], v[156:159], v[208:211], v[36:39]
	v_mfma_f32_16x16x32_bf16 v[28:31], v[160:163], v[204:207], 0
	v_mfma_f32_16x16x32_bf16 v[28:31], v[164:167], v[208:211], v[28:31]
	v_mfma_f32_16x16x32_bf16 v[20:23], v[152:155], v[212:215], 0
	v_mfma_f32_16x16x32_bf16 v[20:23], v[156:159], v[216:219], v[20:23]
	v_mfma_f32_16x16x32_bf16 v[12:15], v[160:163], v[212:215], 0
	v_mfma_f32_16x16x32_bf16 v[12:15], v[164:167], v[216:219], v[12:15]
	v_mfma_f32_16x16x32_bf16 v[48:51], v[168:171], v[188:191], 0
	v_mfma_f32_16x16x32_bf16 v[48:51], v[172:175], v[192:195], v[48:51]
	v_mfma_f32_16x16x32_bf16 v[40:43], v[176:179], v[188:191], 0
	v_mfma_f32_16x16x32_bf16 v[40:43], v[184:187], v[192:195], v[40:43]
	v_mfma_f32_16x16x32_bf16 v[32:35], v[168:171], v[196:199], 0
	v_mfma_f32_16x16x32_bf16 v[32:35], v[172:175], v[200:203], v[32:35]
	v_mfma_f32_16x16x32_bf16 v[24:27], v[176:179], v[196:199], 0
	v_mfma_f32_16x16x32_bf16 v[24:27], v[184:187], v[200:203], v[24:27]
	v_mfma_f32_16x16x32_bf16 v[16:19], v[168:171], v[204:207], 0
	v_mfma_f32_16x16x32_bf16 v[16:19], v[172:175], v[208:211], v[16:19]
	v_mfma_f32_16x16x32_bf16 v[8:11], v[176:179], v[204:207], 0
	v_mfma_f32_16x16x32_bf16 v[8:11], v[184:187], v[208:211], v[8:11]
	v_mfma_f32_16x16x32_bf16 v[4:7], v[168:171], v[212:215], 0
	v_mfma_f32_16x16x32_bf16 v[4:7], v[172:175], v[216:219], v[4:7]
	v_mfma_f32_16x16x32_bf16 v[0:3], v[176:179], v[212:215], 0
	v_mfma_f32_16x16x32_bf16 v[0:3], v[184:187], v[216:219], v[0:3]
	s_setprio 0
	s_barrier
	s_branch .Lmid_gemm3

.LBB0_723:
	s_ashr_i32 s31, s30, 31
	s_lshl_b64 s[36:37], s[30:31], 19
	s_add_u32 s36, s80, s36
	s_addc_u32 s37, s81, s37
	s_and_b64 s[44:45], s[10:11], exec
	s_cselect_b32 s31, s37, s49
	s_cselect_b32 s70, s36, s48
	s_ashr_i32 s19, s18, 31
	s_lshl_b64 s[44:45], s[18:19], 19
	s_add_u32 s44, s56, s44
	s_addc_u32 s45, s57, s45
	s_and_b64 s[54:55], s[10:11], exec
	s_cselect_b32 s19, s45, s53
	s_cselect_b32 s71, s44, s52
	s_cbranch_scc1 .Lnx_4
	s_add_u32 s70, s70, 0x700
	s_addc_u32 s31, s31, 0
	s_add_u32 s71, s71, 0x700
	s_addc_u32 s19, s19, 0
.Lnx_4:
	s_add_u32 s48, s48, 0x40080
	s_addc_u32 s49, s49, 0
	s_add_u32 s72, s52, 0x100
	s_addc_u32 s73, s53, 0
	s_mov_b32 s74, -2
	ds_read_b128 v[140:143], v147
	ds_read_b128 v[150:153], v147 offset:1024
	ds_read_b128 v[154:157], v147 offset:2048
	ds_read_b128 v[158:161], v147 offset:3072
	ds_read_b128 v[162:165], v148
	ds_read_b128 v[166:169], v148 offset:1024
	ds_read_b128 v[170:173], v148 offset:2048
	ds_read_b128 v[174:177], v148 offset:3072
	s_add_u32 s52, s48, 0xfffc0080
	s_addc_u32 s53, s49, -1
	s_cmp_eq_u32 s74, 12
	s_cselect_b32 s55, s31, s53
	s_cselect_b32 s54, s70, s52
	s_cselect_b32 s53, s19, s73
	s_cselect_b32 s52, s71, s72
	v_lshl_add_u64 v[178:179], s[48:49], 0, v[132:133]
	s_add_i32 m0, s47, 0xc000
	ds_read_b128 v[184:187], v149
	ds_read_b128 v[188:191], v149 offset:1024
	ds_read_b128 v[192:195], v149 offset:2048
	ds_read_b128 v[196:199], v149 offset:3072
	ds_read_b128 v[200:203], v149 offset:4096
	ds_read_b128 v[204:207], v149 offset:5120
	ds_read_b128 v[208:211], v149 offset:6144
	ds_read_b128 v[212:215], v149 offset:7168
	global_load_lds_dwordx4 v[178:179], off
	v_lshl_add_u64 v[178:179], s[48:49], 0, v[134:135]
	s_add_i32 m0, s47, 0xe000
	s_nop 0
	global_load_lds_dwordx4 v[178:179], off
	s_waitcnt vmcnt(8)
	s_waitcnt lgkmcnt(0)
	s_barrier
	s_setprio 1
	s_waitcnt lgkmcnt(0)
	v_mfma_f32_16x16x32_bf16 v[124:127], v[140:143], v[184:187], 0
	v_mfma_f32_16x16x32_bf16 v[124:127], v[150:153], v[188:191], v[124:127]
	v_mfma_f32_16x16x32_bf16 v[120:123], v[154:157], v[184:187], 0
	v_mfma_f32_16x16x32_bf16 v[120:123], v[158:161], v[188:191], v[120:123]
	v_mfma_f32_16x16x32_bf16 v[108:111], v[140:143], v[192:195], 0
	v_mfma_f32_16x16x32_bf16 v[108:111], v[150:153], v[196:199], v[108:111]
	v_mfma_f32_16x16x32_bf16 v[104:107], v[154:157], v[192:195], 0
	v_mfma_f32_16x16x32_bf16 v[104:107], v[158:161], v[196:199], v[104:107]
	v_mfma_f32_16x16x32_bf16 v[92:95], v[140:143], v[200:203], 0
	v_mfma_f32_16x16x32_bf16 v[92:95], v[150:153], v[204:207], v[92:95]
	v_mfma_f32_16x16x32_bf16 v[88:91], v[154:157], v[200:203], 0
	v_mfma_f32_16x16x32_bf16 v[88:91], v[158:161], v[204:207], v[88:91]
	v_mfma_f32_16x16x32_bf16 v[76:79], v[140:143], v[208:211], 0
	v_mfma_f32_16x16x32_bf16 v[76:79], v[150:153], v[212:215], v[76:79]
	v_mfma_f32_16x16x32_bf16 v[72:75], v[154:157], v[208:211], 0
	v_mfma_f32_16x16x32_bf16 v[72:75], v[158:161], v[212:215], v[72:75]
	v_mfma_f32_16x16x32_bf16 v[116:119], v[162:165], v[184:187], 0
	v_mfma_f32_16x16x32_bf16 v[116:119], v[166:169], v[188:191], v[116:119]
	v_mfma_f32_16x16x32_bf16 v[112:115], v[170:173], v[184:187], 0
	v_mfma_f32_16x16x32_bf16 v[112:115], v[174:177], v[188:191], v[112:115]
	v_mfma_f32_16x16x32_bf16 v[100:103], v[162:165], v[192:195], 0
	v_mfma_f32_16x16x32_bf16 v[100:103], v[166:169], v[196:199], v[100:103]
	v_mfma_f32_16x16x32_bf16 v[96:99], v[170:173], v[192:195], 0
	v_mfma_f32_16x16x32_bf16 v[96:99], v[174:177], v[196:199], v[96:99]
	v_mfma_f32_16x16x32_bf16 v[84:87], v[162:165], v[200:203], 0
	v_mfma_f32_16x16x32_bf16 v[84:87], v[166:169], v[204:207], v[84:87]
	v_mfma_f32_16x16x32_bf16 v[80:83], v[170:173], v[200:203], 0
	v_mfma_f32_16x16x32_bf16 v[80:83], v[174:177], v[204:207], v[80:83]
	v_mfma_f32_16x16x32_bf16 v[68:71], v[162:165], v[208:211], 0
	v_mfma_f32_16x16x32_bf16 v[68:71], v[166:169], v[212:215], v[68:71]
	v_mfma_f32_16x16x32_bf16 v[64:67], v[170:173], v[208:211], 0
	v_mfma_f32_16x16x32_bf16 v[64:67], v[174:177], v[212:215], v[64:67]
	s_setprio 0
	s_barrier
	s_add_i32 s75, s66, s58
	v_lshl_add_u64 v[178:179], s[52:53], 0, v[130:131]
	s_mov_b32 m0, s75
	ds_read_b128 v[184:187], v149 offset:16384
	ds_read_b128 v[188:191], v149 offset:17408
	ds_read_b128 v[192:195], v149 offset:18432
	ds_read_b128 v[196:199], v149 offset:19456
	ds_read_b128 v[200:203], v149 offset:20480
	ds_read_b128 v[204:207], v149 offset:21504
	ds_read_b128 v[208:211], v149 offset:22528
	ds_read_b128 v[212:215], v149 offset:23552
	global_load_lds_dwordx4 v[178:179], off
	s_add_i32 m0, s75, 0x2000
	s_add_u32 s76, s52, 0x40000
	v_lshl_add_u64 v[216:217], s[52:53], 0, v[128:129]
	s_addc_u32 s77, s53, 0
	s_add_i32 s75, s67, s58
	global_load_lds_dwordx4 v[216:217], off
	v_lshl_add_u64 v[218:219], s[76:77], 0, v[130:131]
	s_mov_b32 m0, s75
	v_lshl_add_u64 v[220:221], s[54:55], 0, v[128:129]
	global_load_lds_dwordx4 v[218:219], off
	v_lshl_add_u64 v[218:219], s[76:77], 0, v[128:129]
	s_add_i32 m0, s75, 0x2000
	s_nop 0
	global_load_lds_dwordx4 v[218:219], off
	v_lshl_add_u64 v[218:219], s[54:55], 0, v[130:131]
	s_mov_b32 m0, s47
	s_nop 0
	global_load_lds_dwordx4 v[218:219], off
	s_mov_b32 m0, s60
	s_nop 0
	global_load_lds_dwordx4 v[220:221], off
	s_waitcnt vmcnt(8)
	s_waitcnt lgkmcnt(0)
	s_barrier
	s_setprio 1
	s_waitcnt lgkmcnt(0)
	v_mfma_f32_16x16x32_bf16 v[60:63], v[140:143], v[184:187], 0
	v_mfma_f32_16x16x32_bf16 v[60:63], v[150:153], v[188:191], v[60:63]
	v_mfma_f32_16x16x32_bf16 v[56:59], v[154:157], v[184:187], 0
	v_mfma_f32_16x16x32_bf16 v[56:59], v[158:161], v[188:191], v[56:59]
	v_mfma_f32_16x16x32_bf16 v[44:47], v[140:143], v[192:195], 0
	v_mfma_f32_16x16x32_bf16 v[44:47], v[150:153], v[196:199], v[44:47]
	v_mfma_f32_16x16x32_bf16 v[40:43], v[154:157], v[192:195], 0
	v_mfma_f32_16x16x32_bf16 v[40:43], v[158:161], v[196:199], v[40:43]
	v_mfma_f32_16x16x32_bf16 v[28:31], v[140:143], v[200:203], 0
	v_mfma_f32_16x16x32_bf16 v[28:31], v[150:153], v[204:207], v[28:31]
	v_mfma_f32_16x16x32_bf16 v[24:27], v[154:157], v[200:203], 0
	v_mfma_f32_16x16x32_bf16 v[24:27], v[158:161], v[204:207], v[24:27]
	v_mfma_f32_16x16x32_bf16 v[12:15], v[140:143], v[208:211], 0
	v_mfma_f32_16x16x32_bf16 v[12:15], v[150:153], v[212:215], v[12:15]
	v_mfma_f32_16x16x32_bf16 v[8:11], v[154:157], v[208:211], 0
	v_mfma_f32_16x16x32_bf16 v[8:11], v[158:161], v[212:215], v[8:11]
	v_mfma_f32_16x16x32_bf16 v[52:55], v[162:165], v[184:187], 0
	v_mfma_f32_16x16x32_bf16 v[52:55], v[166:169], v[188:191], v[52:55]
	v_mfma_f32_16x16x32_bf16 v[48:51], v[170:173], v[184:187], 0
	v_mfma_f32_16x16x32_bf16 v[48:51], v[174:177], v[188:191], v[48:51]
	v_mfma_f32_16x16x32_bf16 v[36:39], v[162:165], v[192:195], 0
	v_mfma_f32_16x16x32_bf16 v[36:39], v[166:169], v[196:199], v[36:39]
	v_mfma_f32_16x16x32_bf16 v[32:35], v[170:173], v[192:195], 0
	v_mfma_f32_16x16x32_bf16 v[32:35], v[174:177], v[196:199], v[32:35]
	v_mfma_f32_16x16x32_bf16 v[20:23], v[162:165], v[200:203], 0
	v_mfma_f32_16x16x32_bf16 v[20:23], v[166:169], v[204:207], v[20:23]
	v_mfma_f32_16x16x32_bf16 v[16:19], v[170:173], v[200:203], 0
	v_mfma_f32_16x16x32_bf16 v[16:19], v[174:177], v[204:207], v[16:19]
	v_mfma_f32_16x16x32_bf16 v[4:7], v[162:165], v[208:211], 0
	v_mfma_f32_16x16x32_bf16 v[4:7], v[166:169], v[212:215], v[4:7]
	v_mfma_f32_16x16x32_bf16 v[0:3], v[170:173], v[208:211], 0
	v_mfma_f32_16x16x32_bf16 v[0:3], v[174:177], v[212:215], v[0:3]
	s_setprio 0
	s_barrier
	s_branch .Lmid_gemm4

.LBB0_803:
	s_cbranch_vccz .Lnx_5
	s_add_u32 s12, s12, 0x1500
	s_addc_u32 s13, s13, 0
	s_add_u32 s48, s48, 0x1500
	s_addc_u32 s49, s49, 0

.LBB0_934:
	s_ashr_i32 s53, s52, 31
	s_lshl_b64 s[54:55], s[52:53], 19
	s_add_u32 s54, s80, s54
	s_addc_u32 s55, s81, s55
	s_and_b64 s[56:57], s[10:11], exec
	s_cselect_b32 s53, s55, s61
	s_cselect_b32 s83, s54, s60
	s_ashr_i32 s49, s48, 31
	s_lshl_b64 s[56:57], s[48:49], 19
	s_add_u32 s56, s66, s56
	s_addc_u32 s57, s67, s57
	s_and_b64 s[64:65], s[10:11], exec
	s_cselect_b32 s49, s57, s63
	s_cselect_b32 s84, s56, s62
	s_cbranch_scc1 .Lnx_6
	s_add_u32 s83, s83, 0x700
	s_addc_u32 s53, s53, 0
	s_add_u32 s84, s84, 0x700
	s_addc_u32 s49, s49, 0
.Lnx_6:
	s_add_u32 s60, s60, 0x40080
	s_addc_u32 s61, s61, 0
	s_add_u32 s85, s62, 0x100
	s_addc_u32 s86, s63, 0
	s_mov_b32 s87, -2
	ds_read_b128 v[152:155], v148
	ds_read_b128 v[156:159], v148 offset:1024
	ds_read_b128 v[160:163], v148 offset:2048
	ds_read_b128 v[164:167], v148 offset:3072
	ds_read_b128 v[168:171], v149
	ds_read_b128 v[172:175], v149 offset:1024
	ds_read_b128 v[176:179], v149 offset:2048
	ds_read_b128 v[184:187], v149 offset:3072
	s_add_u32 s62, s60, 0xfffc0080
	s_addc_u32 s63, s61, -1
	s_cmp_eq_u32 s87, 12
	s_cselect_b32 s65, s53, s63
	s_cselect_b32 s64, s83, s62
	s_cselect_b32 s63, s49, s86
	s_cselect_b32 s62, s84, s85
	v_lshl_add_u64 v[220:221], s[60:61], 0, v[138:139]
	s_add_i32 m0, s69, 0xc000
	ds_read_b128 v[188:191], v150
	ds_read_b128 v[192:195], v150 offset:1024
	ds_read_b128 v[196:199], v150 offset:2048
	ds_read_b128 v[200:203], v150 offset:3072
	ds_read_b128 v[204:207], v150 offset:4096
	ds_read_b128 v[208:211], v150 offset:5120
	ds_read_b128 v[212:215], v150 offset:6144
	ds_read_b128 v[216:219], v150 offset:7168
	global_load_lds_dwordx4 v[220:221], off
	v_lshl_add_u64 v[220:221], s[60:61], 0, v[140:141]
	s_add_i32 m0, s69, 0xe000
	s_nop 0
	global_load_lds_dwordx4 v[220:221], off
	s_waitcnt vmcnt(8)
	s_waitcnt lgkmcnt(0)
	s_barrier
	s_setprio 1
	s_waitcnt lgkmcnt(0)
	v_mfma_f32_16x16x32_bf16 v[124:127], v[152:155], v[188:191], 0
	v_mfma_f32_16x16x32_bf16 v[124:127], v[156:159], v[192:195], v[124:127]
	v_mfma_f32_16x16x32_bf16 v[120:123], v[160:163], v[188:191], 0
	v_mfma_f32_16x16x32_bf16 v[120:123], v[164:167], v[192:195], v[120:123]
	v_mfma_f32_16x16x32_bf16 v[116:119], v[152:155], v[196:199], 0
	v_mfma_f32_16x16x32_bf16 v[116:119], v[156:159], v[200:203], v[116:119]
	v_mfma_f32_16x16x32_bf16 v[112:115], v[160:163], v[196:199], 0
	v_mfma_f32_16x16x32_bf16 v[112:115], v[164:167], v[200:203], v[112:115]
	v_mfma_f32_16x16x32_bf16 v[108:111], v[152:155], v[204:207], 0
	v_mfma_f32_16x16x32_bf16 v[108:111], v[156:159], v[208:211], v[108:111]
	v_mfma_f32_16x16x32_bf16 v[104:107], v[160:163], v[204:207], 0
	v_mfma_f32_16x16x32_bf16 v[104:107], v[164:167], v[208:211], v[104:107]
	v_mfma_f32_16x16x32_bf16 v[100:103], v[152:155], v[212:215], 0
	v_mfma_f32_16x16x32_bf16 v[100:103], v[156:159], v[216:219], v[100:103]
	v_mfma_f32_16x16x32_bf16 v[96:99], v[160:163], v[212:215], 0
	v_mfma_f32_16x16x32_bf16 v[96:99], v[164:167], v[216:219], v[96:99]
	v_mfma_f32_16x16x32_bf16 v[76:79], v[168:171], v[188:191], 0
	v_mfma_f32_16x16x32_bf16 v[76:79], v[172:175], v[192:195], v[76:79]
	v_mfma_f32_16x16x32_bf16 v[68:71], v[176:179], v[188:191], 0
	v_mfma_f32_16x16x32_bf16 v[68:71], v[184:187], v[192:195], v[68:71]
	v_mfma_f32_16x16x32_bf16 v[60:63], v[168:171], v[196:199], 0
	v_mfma_f32_16x16x32_bf16 v[60:63], v[172:175], v[200:203], v[60:63]
	v_mfma_f32_16x16x32_bf16 v[52:55], v[176:179], v[196:199], 0
	v_mfma_f32_16x16x32_bf16 v[52:55], v[184:187], v[200:203], v[52:55]
	v_mfma_f32_16x16x32_bf16 v[44:47], v[168:171], v[204:207], 0
	v_mfma_f32_16x16x32_bf16 v[44:47], v[172:175], v[208:211], v[44:47]
	v_mfma_f32_16x16x32_bf16 v[40:43], v[176:179], v[204:207], 0
	v_mfma_f32_16x16x32_bf16 v[40:43], v[184:187], v[208:211], v[40:43]
	v_mfma_f32_16x16x32_bf16 v[36:39], v[168:171], v[212:215], 0
	v_mfma_f32_16x16x32_bf16 v[36:39], v[172:175], v[216:219], v[36:39]
	v_mfma_f32_16x16x32_bf16 v[32:35], v[176:179], v[212:215], 0
	v_mfma_f32_16x16x32_bf16 v[32:35], v[184:187], v[216:219], v[32:35]
	s_setprio 0
	s_barrier
	s_add_i32 s79, s77, s68
	v_lshl_add_u64 v[220:221], s[62:63], 0, v[130:131]
	s_mov_b32 m0, s79
	ds_read_b128 v[188:191], v150 offset:16384
	ds_read_b128 v[192:195], v150 offset:17408
	ds_read_b128 v[196:199], v150 offset:18432
	ds_read_b128 v[200:203], v150 offset:19456
	ds_read_b128 v[204:207], v150 offset:20480
	ds_read_b128 v[208:211], v150 offset:21504
	ds_read_b128 v[212:215], v150 offset:22528
	ds_read_b128 v[216:219], v150 offset:23552
	global_load_lds_dwordx4 v[220:221], off
	s_add_i32 m0, s79, 0x2000
	s_add_u32 s88, s62, 0x40000
	v_lshl_add_u64 v[222:223], s[62:63], 0, v[134:135]
	s_addc_u32 s89, s63, 0
	s_add_i32 s79, s82, s68
	global_load_lds_dwordx4 v[222:223], off
	v_lshl_add_u64 v[224:225], s[88:89], 0, v[130:131]
	s_mov_b32 m0, s79
	v_lshl_add_u64 v[226:227], s[64:65], 0, v[132:133]
	global_load_lds_dwordx4 v[224:225], off
	v_lshl_add_u64 v[224:225], s[88:89], 0, v[134:135]
	s_add_i32 m0, s79, 0x2000
	s_nop 0
	global_load_lds_dwordx4 v[224:225], off
	v_lshl_add_u64 v[224:225], s[64:65], 0, v[128:129]
	s_mov_b32 m0, s69
	s_nop 0
	global_load_lds_dwordx4 v[224:225], off
	s_mov_b32 m0, s70
	s_nop 0
	global_load_lds_dwordx4 v[226:227], off
	s_waitcnt vmcnt(8)
	s_waitcnt lgkmcnt(0)
	s_barrier
	s_setprio 1
	s_waitcnt lgkmcnt(0)
	v_mfma_f32_16x16x32_bf16 v[92:95], v[152:155], v[188:191], 0
	v_mfma_f32_16x16x32_bf16 v[92:95], v[156:159], v[192:195], v[92:95]
	v_mfma_f32_16x16x32_bf16 v[88:91], v[160:163], v[188:191], 0
	v_mfma_f32_16x16x32_bf16 v[88:91], v[164:167], v[192:195], v[88:91]
	v_mfma_f32_16x16x32_bf16 v[84:87], v[152:155], v[196:199], 0
	v_mfma_f32_16x16x32_bf16 v[84:87], v[156:159], v[200:203], v[84:87]
	v_mfma_f32_16x16x32_bf16 v[80:83], v[160:163], v[196:199], 0
	v_mfma_f32_16x16x32_bf16 v[80:83], v[164:167], v[200:203], v[80:83]
	v_mfma_f32_16x16x32_bf16 v[72:75], v[152:155], v[204:207], 0
	v_mfma_f32_16x16x32_bf16 v[72:75], v[156:159], v[208:211], v[72:75]
	v_mfma_f32_16x16x32_bf16 v[64:67], v[160:163], v[204:207], 0
	v_mfma_f32_16x16x32_bf16 v[64:67], v[164:167], v[208:211], v[64:67]
	v_mfma_f32_16x16x32_bf16 v[56:59], v[152:155], v[212:215], 0
	v_mfma_f32_16x16x32_bf16 v[56:59], v[156:159], v[216:219], v[56:59]
	v_mfma_f32_16x16x32_bf16 v[48:51], v[160:163], v[212:215], 0
	v_mfma_f32_16x16x32_bf16 v[48:51], v[164:167], v[216:219], v[48:51]
	v_mfma_f32_16x16x32_bf16 v[28:31], v[168:171], v[188:191], 0
	v_mfma_f32_16x16x32_bf16 v[28:31], v[172:175], v[192:195], v[28:31]
	v_mfma_f32_16x16x32_bf16 v[24:27], v[176:179], v[188:191], 0
	v_mfma_f32_16x16x32_bf16 v[24:27], v[184:187], v[192:195], v[24:27]
	v_mfma_f32_16x16x32_bf16 v[20:23], v[168:171], v[196:199], 0
	v_mfma_f32_16x16x32_bf16 v[20:23], v[172:175], v[200:203], v[20:23]
	v_mfma_f32_16x16x32_bf16 v[16:19], v[176:179], v[196:199], 0
	v_mfma_f32_16x16x32_bf16 v[16:19], v[184:187], v[200:203], v[16:19]
	v_mfma_f32_16x16x32_bf16 v[12:15], v[168:171], v[204:207], 0
	v_mfma_f32_16x16x32_bf16 v[12:15], v[172:175], v[208:211], v[12:15]
	v_mfma_f32_16x16x32_bf16 v[8:11], v[176:179], v[204:207], 0
	v_mfma_f32_16x16x32_bf16 v[8:11], v[184:187], v[208:211], v[8:11]
	v_mfma_f32_16x16x32_bf16 v[4:7], v[168:171], v[212:215], 0
	v_mfma_f32_16x16x32_bf16 v[4:7], v[172:175], v[216:219], v[4:7]
	v_mfma_f32_16x16x32_bf16 v[0:3], v[176:179], v[212:215], 0
	v_mfma_f32_16x16x32_bf16 v[0:3], v[184:187], v[216:219], v[0:3]
	s_setprio 0
	s_barrier
	s_branch .Lmid_gemm6

.LBB0_950:
	s_ashr_i32 s37, s36, 31
	s_lshl_b64 s[44:45], s[36:37], 19
	s_add_u32 s44, s80, s44
	s_addc_u32 s45, s81, s45
	s_and_b64 s[46:47], s[10:11], exec
	s_cselect_b32 s37, s45, s53
	s_cselect_b32 s72, s44, s52
	s_ashr_i32 s19, s18, 31
	s_lshl_b64 s[46:47], s[18:19], 19
	s_add_u32 s46, s58, s46
	s_addc_u32 s47, s59, s47
	s_and_b64 s[56:57], s[10:11], exec
	s_cselect_b32 s19, s47, s55
	s_cselect_b32 s73, s46, s54
	s_cbranch_scc1 .Lnx_7
	s_add_u32 s72, s72, 0x700
	s_addc_u32 s37, s37, 0
	s_add_u32 s73, s73, 0x700
	s_addc_u32 s19, s19, 0
.Lnx_7:
	s_add_u32 s52, s52, 0x40080
	s_addc_u32 s53, s53, 0
	s_add_u32 s74, s54, 0x100
	s_addc_u32 s75, s55, 0
	s_mov_b32 s76, -2
	ds_read_b128 v[140:143], v147
	ds_read_b128 v[150:153], v147 offset:1024
	ds_read_b128 v[154:157], v147 offset:2048
	ds_read_b128 v[158:161], v147 offset:3072
	ds_read_b128 v[162:165], v148
	ds_read_b128 v[166:169], v148 offset:1024
	ds_read_b128 v[170:173], v148 offset:2048
	ds_read_b128 v[174:177], v148 offset:3072
	s_add_u32 s54, s52, 0xfffc0080
	s_addc_u32 s55, s53, -1
	s_cmp_eq_u32 s76, 12
	s_cselect_b32 s57, s37, s55
	s_cselect_b32 s56, s72, s54
	s_cselect_b32 s55, s19, s75
	s_cselect_b32 s54, s73, s74
	v_lshl_add_u64 v[178:179], s[52:53], 0, v[132:133]
	s_add_i32 m0, s49, 0xc000
	ds_read_b128 v[184:187], v149
	ds_read_b128 v[188:191], v149 offset:1024
	ds_read_b128 v[192:195], v149 offset:2048
	ds_read_b128 v[196:199], v149 offset:3072
	ds_read_b128 v[200:203], v149 offset:4096
	ds_read_b128 v[204:207], v149 offset:5120
	ds_read_b128 v[208:211], v149 offset:6144
	ds_read_b128 v[212:215], v149 offset:7168
	global_load_lds_dwordx4 v[178:179], off
	v_lshl_add_u64 v[178:179], s[52:53], 0, v[134:135]
	s_add_i32 m0, s49, 0xe000
	s_nop 0
	global_load_lds_dwordx4 v[178:179], off
	s_waitcnt vmcnt(8)
	s_waitcnt lgkmcnt(0)
	s_barrier
	s_setprio 1
	s_waitcnt lgkmcnt(0)
	v_mfma_f32_16x16x32_bf16 v[124:127], v[140:143], v[184:187], 0
	v_mfma_f32_16x16x32_bf16 v[124:127], v[150:153], v[188:191], v[124:127]
	v_mfma_f32_16x16x32_bf16 v[120:123], v[154:157], v[184:187], 0
	v_mfma_f32_16x16x32_bf16 v[120:123], v[158:161], v[188:191], v[120:123]
	v_mfma_f32_16x16x32_bf16 v[108:111], v[140:143], v[192:195], 0
	v_mfma_f32_16x16x32_bf16 v[108:111], v[150:153], v[196:199], v[108:111]
	v_mfma_f32_16x16x32_bf16 v[104:107], v[154:157], v[192:195], 0
	v_mfma_f32_16x16x32_bf16 v[104:107], v[158:161], v[196:199], v[104:107]
	v_mfma_f32_16x16x32_bf16 v[92:95], v[140:143], v[200:203], 0
	v_mfma_f32_16x16x32_bf16 v[92:95], v[150:153], v[204:207], v[92:95]
	v_mfma_f32_16x16x32_bf16 v[88:91], v[154:157], v[200:203], 0
	v_mfma_f32_16x16x32_bf16 v[88:91], v[158:161], v[204:207], v[88:91]
	v_mfma_f32_16x16x32_bf16 v[76:79], v[140:143], v[208:211], 0
	v_mfma_f32_16x16x32_bf16 v[76:79], v[150:153], v[212:215], v[76:79]
	v_mfma_f32_16x16x32_bf16 v[72:75], v[154:157], v[208:211], 0
	v_mfma_f32_16x16x32_bf16 v[72:75], v[158:161], v[212:215], v[72:75]
	v_mfma_f32_16x16x32_bf16 v[116:119], v[162:165], v[184:187], 0
	v_mfma_f32_16x16x32_bf16 v[116:119], v[166:169], v[188:191], v[116:119]
	v_mfma_f32_16x16x32_bf16 v[112:115], v[170:173], v[184:187], 0
	v_mfma_f32_16x16x32_bf16 v[112:115], v[174:177], v[188:191], v[112:115]
	v_mfma_f32_16x16x32_bf16 v[100:103], v[162:165], v[192:195], 0
	v_mfma_f32_16x16x32_bf16 v[100:103], v[166:169], v[196:199], v[100:103]
	v_mfma_f32_16x16x32_bf16 v[96:99], v[170:173], v[192:195], 0
	v_mfma_f32_16x16x32_bf16 v[96:99], v[174:177], v[196:199], v[96:99]
	v_mfma_f32_16x16x32_bf16 v[84:87], v[162:165], v[200:203], 0
	v_mfma_f32_16x16x32_bf16 v[84:87], v[166:169], v[204:207], v[84:87]
	v_mfma_f32_16x16x32_bf16 v[80:83], v[170:173], v[200:203], 0
	v_mfma_f32_16x16x32_bf16 v[80:83], v[174:177], v[204:207], v[80:83]
	v_mfma_f32_16x16x32_bf16 v[68:71], v[162:165], v[208:211], 0
	v_mfma_f32_16x16x32_bf16 v[68:71], v[166:169], v[212:215], v[68:71]
	v_mfma_f32_16x16x32_bf16 v[64:67], v[170:173], v[208:211], 0
	v_mfma_f32_16x16x32_bf16 v[64:67], v[174:177], v[212:215], v[64:67]
	s_setprio 0
	s_barrier
	s_add_i32 s77, s68, s60
	v_lshl_add_u64 v[178:179], s[54:55], 0, v[130:131]
	s_mov_b32 m0, s77
	ds_read_b128 v[184:187], v149 offset:16384
	ds_read_b128 v[188:191], v149 offset:17408
	ds_read_b128 v[192:195], v149 offset:18432
	ds_read_b128 v[196:199], v149 offset:19456
	ds_read_b128 v[200:203], v149 offset:20480
	ds_read_b128 v[204:207], v149 offset:21504
	ds_read_b128 v[208:211], v149 offset:22528
	ds_read_b128 v[212:215], v149 offset:23552
	global_load_lds_dwordx4 v[178:179], off
	s_add_i32 m0, s77, 0x2000
	s_add_u32 s82, s54, 0x40000
	v_lshl_add_u64 v[216:217], s[54:55], 0, v[128:129]
	s_addc_u32 s83, s55, 0
	s_add_i32 s77, s69, s60
	global_load_lds_dwordx4 v[216:217], off
	v_lshl_add_u64 v[218:219], s[82:83], 0, v[130:131]
	s_mov_b32 m0, s77
	v_lshl_add_u64 v[220:221], s[56:57], 0, v[128:129]
	global_load_lds_dwordx4 v[218:219], off
	v_lshl_add_u64 v[218:219], s[82:83], 0, v[128:129]
	s_add_i32 m0, s77, 0x2000
	s_nop 0
	global_load_lds_dwordx4 v[218:219], off
	v_lshl_add_u64 v[218:219], s[56:57], 0, v[130:131]
	s_mov_b32 m0, s49
	s_nop 0
	global_load_lds_dwordx4 v[218:219], off
	s_mov_b32 m0, s62
	s_nop 0
	global_load_lds_dwordx4 v[220:221], off
	s_waitcnt vmcnt(8)
	s_waitcnt lgkmcnt(0)
	s_barrier
	s_setprio 1
	s_waitcnt lgkmcnt(0)
	v_mfma_f32_16x16x32_bf16 v[60:63], v[140:143], v[184:187], 0
	v_mfma_f32_16x16x32_bf16 v[60:63], v[150:153], v[188:191], v[60:63]
	v_mfma_f32_16x16x32_bf16 v[56:59], v[154:157], v[184:187], 0
	v_mfma_f32_16x16x32_bf16 v[56:59], v[158:161], v[188:191], v[56:59]
	v_mfma_f32_16x16x32_bf16 v[44:47], v[140:143], v[192:195], 0
	v_mfma_f32_16x16x32_bf16 v[44:47], v[150:153], v[196:199], v[44:47]
	v_mfma_f32_16x16x32_bf16 v[40:43], v[154:157], v[192:195], 0
	v_mfma_f32_16x16x32_bf16 v[40:43], v[158:161], v[196:199], v[40:43]
	v_mfma_f32_16x16x32_bf16 v[28:31], v[140:143], v[200:203], 0
	v_mfma_f32_16x16x32_bf16 v[28:31], v[150:153], v[204:207], v[28:31]
	v_mfma_f32_16x16x32_bf16 v[24:27], v[154:157], v[200:203], 0
	v_mfma_f32_16x16x32_bf16 v[24:27], v[158:161], v[204:207], v[24:27]
	v_mfma_f32_16x16x32_bf16 v[12:15], v[140:143], v[208:211], 0
	v_mfma_f32_16x16x32_bf16 v[12:15], v[150:153], v[212:215], v[12:15]
	v_mfma_f32_16x16x32_bf16 v[8:11], v[154:157], v[208:211], 0
	v_mfma_f32_16x16x32_bf16 v[8:11], v[158:161], v[212:215], v[8:11]
	v_mfma_f32_16x16x32_bf16 v[52:55], v[162:165], v[184:187], 0
	v_mfma_f32_16x16x32_bf16 v[52:55], v[166:169], v[188:191], v[52:55]
	v_mfma_f32_16x16x32_bf16 v[48:51], v[170:173], v[184:187], 0
	v_mfma_f32_16x16x32_bf16 v[48:51], v[174:177], v[188:191], v[48:51]
	v_mfma_f32_16x16x32_bf16 v[36:39], v[162:165], v[192:195], 0
	v_mfma_f32_16x16x32_bf16 v[36:39], v[166:169], v[196:199], v[36:39]
	v_mfma_f32_16x16x32_bf16 v[32:35], v[170:173], v[192:195], 0
	v_mfma_f32_16x16x32_bf16 v[32:35], v[174:177], v[196:199], v[32:35]
	v_mfma_f32_16x16x32_bf16 v[20:23], v[162:165], v[200:203], 0
	v_mfma_f32_16x16x32_bf16 v[20:23], v[166:169], v[204:207], v[20:23]
	v_mfma_f32_16x16x32_bf16 v[16:19], v[170:173], v[200:203], 0
	v_mfma_f32_16x16x32_bf16 v[16:19], v[174:177], v[204:207], v[16:19]
	v_mfma_f32_16x16x32_bf16 v[4:7], v[162:165], v[208:211], 0
	v_mfma_f32_16x16x32_bf16 v[4:7], v[166:169], v[212:215], v[4:7]
	v_mfma_f32_16x16x32_bf16 v[0:3], v[170:173], v[208:211], 0
	v_mfma_f32_16x16x32_bf16 v[0:3], v[174:177], v[212:215], v[0:3]
	s_setprio 0
	s_barrier
	s_branch .Lmid_gemm7

.LBB0_1030:
	s_cbranch_vccz .Lnx_8
	s_add_u32 s12, s12, 0x1500
	s_addc_u32 s13, s13, 0
	s_add_u32 s52, s52, 0x1500
	s_addc_u32 s53, s53, 0

.Lnx_9:
	s_add_u32 s60, s60, 0x40080
	s_addc_u32 s61, s61, 0
	s_add_u32 s85, s62, 0x100
	s_addc_u32 s86, s63, 0
	s_mov_b32 s87, -2
	ds_read_b128 v[152:155], v148
	ds_read_b128 v[156:159], v148 offset:1024
	ds_read_b128 v[160:163], v148 offset:2048
	ds_read_b128 v[164:167], v148 offset:3072
	ds_read_b128 v[168:171], v149
	ds_read_b128 v[172:175], v149 offset:1024
	ds_read_b128 v[176:179], v149 offset:2048
	ds_read_b128 v[184:187], v149 offset:3072
	s_add_u32 s62, s60, 0xfffc0080
	s_addc_u32 s63, s61, -1
	s_cmp_eq_u32 s87, 12
	s_cselect_b32 s65, s53, s63
	s_cselect_b32 s64, s83, s62
	s_cselect_b32 s63, s49, s86
	s_cselect_b32 s62, s84, s85
	v_lshl_add_u64 v[220:221], s[60:61], 0, v[138:139]
	s_add_i32 m0, s69, 0xc000
	ds_read_b128 v[188:191], v150
	ds_read_b128 v[192:195], v150 offset:1024
	ds_read_b128 v[196:199], v150 offset:2048
	ds_read_b128 v[200:203], v150 offset:3072
	ds_read_b128 v[204:207], v150 offset:4096
	ds_read_b128 v[208:211], v150 offset:5120
	ds_read_b128 v[212:215], v150 offset:6144
	ds_read_b128 v[216:219], v150 offset:7168
	global_load_lds_dwordx4 v[220:221], off
	v_lshl_add_u64 v[220:221], s[60:61], 0, v[140:141]
	s_add_i32 m0, s69, 0xe000
	s_nop 0
	global_load_lds_dwordx4 v[220:221], off
	s_waitcnt vmcnt(8)
	s_waitcnt lgkmcnt(0)
	s_barrier
	s_setprio 1
	s_waitcnt lgkmcnt(0)
	v_mfma_f32_16x16x32_bf16 v[124:127], v[152:155], v[188:191], 0
	v_mfma_f32_16x16x32_bf16 v[124:127], v[156:159], v[192:195], v[124:127]
	v_mfma_f32_16x16x32_bf16 v[120:123], v[160:163], v[188:191], 0
	v_mfma_f32_16x16x32_bf16 v[120:123], v[164:167], v[192:195], v[120:123]
	v_mfma_f32_16x16x32_bf16 v[116:119], v[152:155], v[196:199], 0
	v_mfma_f32_16x16x32_bf16 v[116:119], v[156:159], v[200:203], v[116:119]
	v_mfma_f32_16x16x32_bf16 v[112:115], v[160:163], v[196:199], 0
	v_mfma_f32_16x16x32_bf16 v[112:115], v[164:167], v[200:203], v[112:115]
	v_mfma_f32_16x16x32_bf16 v[108:111], v[152:155], v[204:207], 0
	v_mfma_f32_16x16x32_bf16 v[108:111], v[156:159], v[208:211], v[108:111]
	v_mfma_f32_16x16x32_bf16 v[104:107], v[160:163], v[204:207], 0
	v_mfma_f32_16x16x32_bf16 v[104:107], v[164:167], v[208:211], v[104:107]
	v_mfma_f32_16x16x32_bf16 v[100:103], v[152:155], v[212:215], 0
	v_mfma_f32_16x16x32_bf16 v[100:103], v[156:159], v[216:219], v[100:103]
	v_mfma_f32_16x16x32_bf16 v[96:99], v[160:163], v[212:215], 0
	v_mfma_f32_16x16x32_bf16 v[96:99], v[164:167], v[216:219], v[96:99]
	v_mfma_f32_16x16x32_bf16 v[68:71], v[168:171], v[188:191], 0
	v_mfma_f32_16x16x32_bf16 v[68:71], v[172:175], v[192:195], v[68:71]
	v_mfma_f32_16x16x32_bf16 v[64:67], v[176:179], v[188:191], 0
	v_mfma_f32_16x16x32_bf16 v[64:67], v[184:187], v[192:195], v[64:67]
	v_mfma_f32_16x16x32_bf16 v[52:55], v[168:171], v[196:199], 0
	v_mfma_f32_16x16x32_bf16 v[52:55], v[172:175], v[200:203], v[52:55]
	v_mfma_f32_16x16x32_bf16 v[48:51], v[176:179], v[196:199], 0
	v_mfma_f32_16x16x32_bf16 v[48:51], v[184:187], v[200:203], v[48:51]
	v_mfma_f32_16x16x32_bf16 v[44:47], v[168:171], v[204:207], 0
	v_mfma_f32_16x16x32_bf16 v[44:47], v[172:175], v[208:211], v[44:47]
	v_mfma_f32_16x16x32_bf16 v[40:43], v[176:179], v[204:207], 0
	v_mfma_f32_16x16x32_bf16 v[40:43], v[184:187], v[208:211], v[40:43]
	v_mfma_f32_16x16x32_bf16 v[36:39], v[168:171], v[212:215], 0
	v_mfma_f32_16x16x32_bf16 v[36:39], v[172:175], v[216:219], v[36:39]
	v_mfma_f32_16x16x32_bf16 v[32:35], v[176:179], v[212:215], 0
	v_mfma_f32_16x16x32_bf16 v[32:35], v[184:187], v[216:219], v[32:35]
	s_setprio 0
	s_barrier
	s_add_i32 s79, s77, s68
	v_lshl_add_u64 v[220:221], s[62:63], 0, v[130:131]
	s_mov_b32 m0, s79
	ds_read_b128 v[188:191], v150 offset:16384
	ds_read_b128 v[192:195], v150 offset:17408
	ds_read_b128 v[196:199], v150 offset:18432
	ds_read_b128 v[200:203], v150 offset:19456
	ds_read_b128 v[204:207], v150 offset:20480
	ds_read_b128 v[208:211], v150 offset:21504
	ds_read_b128 v[212:215], v150 offset:22528
	ds_read_b128 v[216:219], v150 offset:23552
	global_load_lds_dwordx4 v[220:221], off
	s_add_i32 m0, s79, 0x2000
	s_add_u32 s88, s62, 0x40000
	v_lshl_add_u64 v[222:223], s[62:63], 0, v[134:135]
	s_addc_u32 s89, s63, 0
	s_add_i32 s79, s82, s68
	global_load_lds_dwordx4 v[222:223], off
	v_lshl_add_u64 v[224:225], s[88:89], 0, v[130:131]
	s_mov_b32 m0, s79
	v_lshl_add_u64 v[226:227], s[64:65], 0, v[132:133]
	global_load_lds_dwordx4 v[224:225], off
	v_lshl_add_u64 v[224:225], s[88:89], 0, v[134:135]
	s_add_i32 m0, s79, 0x2000
	s_nop 0
	global_load_lds_dwordx4 v[224:225], off
	v_lshl_add_u64 v[224:225], s[64:65], 0, v[128:129]
	s_mov_b32 m0, s69
	s_nop 0
	global_load_lds_dwordx4 v[224:225], off
	s_mov_b32 m0, s70
	s_nop 0
	global_load_lds_dwordx4 v[226:227], off
	s_waitcnt vmcnt(8)
	s_waitcnt lgkmcnt(0)
	s_barrier
	s_setprio 1
	s_waitcnt lgkmcnt(0)
	v_mfma_f32_16x16x32_bf16 v[92:95], v[152:155], v[188:191], 0
	v_mfma_f32_16x16x32_bf16 v[92:95], v[156:159], v[192:195], v[92:95]
	v_mfma_f32_16x16x32_bf16 v[88:91], v[160:163], v[188:191], 0
	v_mfma_f32_16x16x32_bf16 v[88:91], v[164:167], v[192:195], v[88:91]
	v_mfma_f32_16x16x32_bf16 v[84:87], v[152:155], v[196:199], 0
	v_mfma_f32_16x16x32_bf16 v[84:87], v[156:159], v[200:203], v[84:87]
	v_mfma_f32_16x16x32_bf16 v[80:83], v[160:163], v[196:199], 0
	v_mfma_f32_16x16x32_bf16 v[80:83], v[164:167], v[200:203], v[80:83]
	v_mfma_f32_16x16x32_bf16 v[76:79], v[152:155], v[204:207], 0
	v_mfma_f32_16x16x32_bf16 v[76:79], v[156:159], v[208:211], v[76:79]
	v_mfma_f32_16x16x32_bf16 v[72:75], v[160:163], v[204:207], 0
	v_mfma_f32_16x16x32_bf16 v[72:75], v[164:167], v[208:211], v[72:75]
	v_mfma_f32_16x16x32_bf16 v[60:63], v[152:155], v[212:215], 0
	v_mfma_f32_16x16x32_bf16 v[60:63], v[156:159], v[216:219], v[60:63]
	v_mfma_f32_16x16x32_bf16 v[56:59], v[160:163], v[212:215], 0
	v_mfma_f32_16x16x32_bf16 v[56:59], v[164:167], v[216:219], v[56:59]
	v_mfma_f32_16x16x32_bf16 v[28:31], v[168:171], v[188:191], 0
	v_mfma_f32_16x16x32_bf16 v[28:31], v[172:175], v[192:195], v[28:31]
	v_mfma_f32_16x16x32_bf16 v[24:27], v[176:179], v[188:191], 0
	v_mfma_f32_16x16x32_bf16 v[24:27], v[184:187], v[192:195], v[24:27]
	v_mfma_f32_16x16x32_bf16 v[20:23], v[168:171], v[196:199], 0
	v_mfma_f32_16x16x32_bf16 v[20:23], v[172:175], v[200:203], v[20:23]
	v_mfma_f32_16x16x32_bf16 v[16:19], v[176:179], v[196:199], 0
	v_mfma_f32_16x16x32_bf16 v[16:19], v[184:187], v[200:203], v[16:19]
	v_mfma_f32_16x16x32_bf16 v[12:15], v[168:171], v[204:207], 0
	v_mfma_f32_16x16x32_bf16 v[12:15], v[172:175], v[208:211], v[12:15]
	v_mfma_f32_16x16x32_bf16 v[8:11], v[176:179], v[204:207], 0
	v_mfma_f32_16x16x32_bf16 v[8:11], v[184:187], v[208:211], v[8:11]
	v_mfma_f32_16x16x32_bf16 v[4:7], v[168:171], v[212:215], 0
	v_mfma_f32_16x16x32_bf16 v[4:7], v[172:175], v[216:219], v[4:7]
	v_mfma_f32_16x16x32_bf16 v[0:3], v[176:179], v[212:215], 0
	v_mfma_f32_16x16x32_bf16 v[0:3], v[184:187], v[216:219], v[0:3]
	s_setprio 0
	s_barrier
	s_branch .Lmid_gemm9

.LBB0_1310:
	s_ashr_i32 s49, s48, 31
	s_lshl_b64 s[50:51], s[48:49], 19
	s_add_u32 s50, s38, s50
	s_addc_u32 s51, s39, s51
	s_and_b64 s[52:53], s[10:11], exec
	s_cselect_b32 s49, s51, s57
	s_cselect_b32 s82, s50, s56
	s_ashr_i32 s47, s46, 31
	s_lshl_b64 s[52:53], s[46:47], 19
	s_add_u32 s52, s62, s52
	s_addc_u32 s53, s63, s53
	s_and_b64 s[60:61], s[10:11], exec
	s_cselect_b32 s47, s53, s59
	s_cselect_b32 s83, s52, s58
	s_cbranch_scc1 .Lnx_10
	s_add_u32 s82, s82, 0x700
	s_addc_u32 s49, s49, 0
	s_add_u32 s83, s83, 0x700
	s_addc_u32 s47, s47, 0
.Lnx_10:
	s_add_u32 s56, s56, 0x40080
	s_addc_u32 s57, s57, 0
	s_add_u32 s84, s58, 0x100
	s_addc_u32 s85, s59, 0
	s_mov_b32 s86, -2
	ds_read_b128 v[152:155], v149
	ds_read_b128 v[156:159], v149 offset:1024
	ds_read_b128 v[160:163], v149 offset:2048
	ds_read_b128 v[164:167], v149 offset:3072
	ds_read_b128 v[168:171], v150
	ds_read_b128 v[172:175], v150 offset:1024
	ds_read_b128 v[176:179], v150 offset:2048
	ds_read_b128 v[184:187], v150 offset:3072
	s_add_u32 s58, s56, 0xfffc0080
	s_addc_u32 s59, s57, -1
	s_cmp_eq_u32 s86, 12
	s_cselect_b32 s61, s49, s59
	s_cselect_b32 s60, s82, s58
	s_cselect_b32 s59, s47, s85
	s_cselect_b32 s58, s83, s84
	v_lshl_add_u64 v[144:145], s[56:57], 0, v[136:137]
	s_add_i32 m0, s55, 0xc000
	ds_read_b128 v[188:191], v151
	ds_read_b128 v[192:195], v151 offset:1024
	ds_read_b128 v[196:199], v151 offset:2048
	ds_read_b128 v[200:203], v151 offset:3072
	ds_read_b128 v[204:207], v151 offset:4096
	ds_read_b128 v[208:211], v151 offset:5120
	ds_read_b128 v[212:215], v151 offset:6144
	ds_read_b128 v[216:219], v151 offset:7168
	global_load_lds_dwordx4 v[144:145], off
	v_lshl_add_u64 v[144:145], s[56:57], 0, v[138:139]
	s_add_i32 m0, s55, 0xe000
	s_nop 0
	global_load_lds_dwordx4 v[144:145], off
	s_waitcnt vmcnt(8)
	s_waitcnt lgkmcnt(0)
	s_barrier
	s_setprio 1
	s_waitcnt lgkmcnt(0)
	v_mfma_f32_16x16x32_bf16 v[124:127], v[152:155], v[188:191], 0
	v_mfma_f32_16x16x32_bf16 v[124:127], v[156:159], v[192:195], v[124:127]
	v_mfma_f32_16x16x32_bf16 v[120:123], v[160:163], v[188:191], 0
	v_mfma_f32_16x16x32_bf16 v[120:123], v[164:167], v[192:195], v[120:123]
	v_mfma_f32_16x16x32_bf16 v[116:119], v[152:155], v[196:199], 0
	v_mfma_f32_16x16x32_bf16 v[116:119], v[156:159], v[200:203], v[116:119]
	v_mfma_f32_16x16x32_bf16 v[108:111], v[160:163], v[196:199], 0
	v_mfma_f32_16x16x32_bf16 v[108:111], v[164:167], v[200:203], v[108:111]
	v_mfma_f32_16x16x32_bf16 v[100:103], v[152:155], v[204:207], 0
	v_mfma_f32_16x16x32_bf16 v[100:103], v[156:159], v[208:211], v[100:103]
	v_mfma_f32_16x16x32_bf16 v[92:95], v[160:163], v[204:207], 0
	v_mfma_f32_16x16x32_bf16 v[92:95], v[164:167], v[208:211], v[92:95]
	v_mfma_f32_16x16x32_bf16 v[84:87], v[152:155], v[212:215], 0
	v_mfma_f32_16x16x32_bf16 v[84:87], v[156:159], v[216:219], v[84:87]
	v_mfma_f32_16x16x32_bf16 v[76:79], v[160:163], v[212:215], 0
	v_mfma_f32_16x16x32_bf16 v[76:79], v[164:167], v[216:219], v[76:79]
	v_mfma_f32_16x16x32_bf16 v[112:115], v[168:171], v[188:191], 0
	v_mfma_f32_16x16x32_bf16 v[112:115], v[172:175], v[192:195], v[112:115]
	v_mfma_f32_16x16x32_bf16 v[104:107], v[176:179], v[188:191], 0
	v_mfma_f32_16x16x32_bf16 v[104:107], v[184:187], v[192:195], v[104:107]
	v_mfma_f32_16x16x32_bf16 v[96:99], v[168:171], v[196:199], 0
	v_mfma_f32_16x16x32_bf16 v[96:99], v[172:175], v[200:203], v[96:99]
	v_mfma_f32_16x16x32_bf16 v[88:91], v[176:179], v[196:199], 0
	v_mfma_f32_16x16x32_bf16 v[88:91], v[184:187], v[200:203], v[88:91]
	v_mfma_f32_16x16x32_bf16 v[80:83], v[168:171], v[204:207], 0
	v_mfma_f32_16x16x32_bf16 v[80:83], v[172:175], v[208:211], v[80:83]
	v_mfma_f32_16x16x32_bf16 v[72:75], v[176:179], v[204:207], 0
	v_mfma_f32_16x16x32_bf16 v[72:75], v[184:187], v[208:211], v[72:75]
	v_mfma_f32_16x16x32_bf16 v[68:71], v[168:171], v[212:215], 0
	v_mfma_f32_16x16x32_bf16 v[68:71], v[172:175], v[216:219], v[68:71]
	v_mfma_f32_16x16x32_bf16 v[64:67], v[176:179], v[212:215], 0
	v_mfma_f32_16x16x32_bf16 v[64:67], v[184:187], v[216:219], v[64:67]
	s_setprio 0
	s_barrier
	s_add_i32 s79, s71, s64
	v_lshl_add_u64 v[144:145], s[58:59], 0, v[130:131]
	s_mov_b32 m0, s79
	ds_read_b128 v[188:191], v151 offset:16384
	ds_read_b128 v[192:195], v151 offset:17408
	ds_read_b128 v[196:199], v151 offset:18432
	ds_read_b128 v[200:203], v151 offset:19456
	ds_read_b128 v[204:207], v151 offset:20480
	ds_read_b128 v[208:211], v151 offset:21504
	ds_read_b128 v[212:215], v151 offset:22528
	ds_read_b128 v[216:219], v151 offset:23552
	global_load_lds_dwordx4 v[144:145], off
	s_add_i32 m0, s79, 0x2000
	s_add_u32 s88, s58, 0x40000
	v_lshl_add_u64 v[220:221], s[58:59], 0, v[134:135]
	s_addc_u32 s89, s59, 0
	s_add_i32 s79, s72, s64
	global_load_lds_dwordx4 v[220:221], off
	v_lshl_add_u64 v[222:223], s[88:89], 0, v[130:131]
	s_mov_b32 m0, s79
	v_lshl_add_u64 v[224:225], s[60:61], 0, v[132:133]
	global_load_lds_dwordx4 v[222:223], off
	v_lshl_add_u64 v[222:223], s[88:89], 0, v[134:135]
	s_add_i32 m0, s79, 0x2000
	s_nop 0
	global_load_lds_dwordx4 v[222:223], off
	v_lshl_add_u64 v[222:223], s[60:61], 0, v[128:129]
	s_mov_b32 m0, s55
	s_nop 0
	global_load_lds_dwordx4 v[222:223], off
	s_mov_b32 m0, s65
	s_nop 0
	global_load_lds_dwordx4 v[224:225], off
	s_waitcnt vmcnt(8)
	s_waitcnt lgkmcnt(0)
	s_barrier
	s_setprio 1
	s_waitcnt lgkmcnt(0)
	v_mfma_f32_16x16x32_bf16 v[60:63], v[152:155], v[188:191], 0
	v_mfma_f32_16x16x32_bf16 v[60:63], v[156:159], v[192:195], v[60:63]
	v_mfma_f32_16x16x32_bf16 v[56:59], v[160:163], v[188:191], 0
	v_mfma_f32_16x16x32_bf16 v[56:59], v[164:167], v[192:195], v[56:59]
	v_mfma_f32_16x16x32_bf16 v[52:55], v[152:155], v[196:199], 0
	v_mfma_f32_16x16x32_bf16 v[52:55], v[156:159], v[200:203], v[52:55]
	v_mfma_f32_16x16x32_bf16 v[44:47], v[160:163], v[196:199], 0
	v_mfma_f32_16x16x32_bf16 v[44:47], v[164:167], v[200:203], v[44:47]
	v_mfma_f32_16x16x32_bf16 v[36:39], v[152:155], v[204:207], 0
	v_mfma_f32_16x16x32_bf16 v[36:39], v[156:159], v[208:211], v[36:39]
	v_mfma_f32_16x16x32_bf16 v[28:31], v[160:163], v[204:207], 0
	v_mfma_f32_16x16x32_bf16 v[28:31], v[164:167], v[208:211], v[28:31]
	v_mfma_f32_16x16x32_bf16 v[20:23], v[152:155], v[212:215], 0
	v_mfma_f32_16x16x32_bf16 v[20:23], v[156:159], v[216:219], v[20:23]
	v_mfma_f32_16x16x32_bf16 v[12:15], v[160:163], v[212:215], 0
	v_mfma_f32_16x16x32_bf16 v[12:15], v[164:167], v[216:219], v[12:15]
	v_mfma_f32_16x16x32_bf16 v[48:51], v[168:171], v[188:191], 0
	v_mfma_f32_16x16x32_bf16 v[48:51], v[172:175], v[192:195], v[48:51]
	v_mfma_f32_16x16x32_bf16 v[40:43], v[176:179], v[188:191], 0
	v_mfma_f32_16x16x32_bf16 v[40:43], v[184:187], v[192:195], v[40:43]
	v_mfma_f32_16x16x32_bf16 v[32:35], v[168:171], v[196:199], 0
	v_mfma_f32_16x16x32_bf16 v[32:35], v[172:175], v[200:203], v[32:35]
	v_mfma_f32_16x16x32_bf16 v[24:27], v[176:179], v[196:199], 0
	v_mfma_f32_16x16x32_bf16 v[24:27], v[184:187], v[200:203], v[24:27]
	v_mfma_f32_16x16x32_bf16 v[16:19], v[168:171], v[204:207], 0
	v_mfma_f32_16x16x32_bf16 v[16:19], v[172:175], v[208:211], v[16:19]
	v_mfma_f32_16x16x32_bf16 v[8:11], v[176:179], v[204:207], 0
	v_mfma_f32_16x16x32_bf16 v[8:11], v[184:187], v[208:211], v[8:11]
	v_mfma_f32_16x16x32_bf16 v[4:7], v[168:171], v[212:215], 0
	v_mfma_f32_16x16x32_bf16 v[4:7], v[172:175], v[216:219], v[4:7]
	v_mfma_f32_16x16x32_bf16 v[0:3], v[176:179], v[212:215], 0
	v_mfma_f32_16x16x32_bf16 v[0:3], v[184:187], v[216:219], v[0:3]
	s_setprio 0
	s_barrier
	s_branch .Lmid_gemm10

.LBB0_1433:
	s_ashr_i32 s19, s18, 31
	s_lshl_b64 s[30:31], s[18:19], 19
	s_add_u32 s30, s80, s30
	s_addc_u32 s31, s81, s31
	s_and_b64 s[36:37], s[8:9], exec
	s_cselect_b32 s19, s31, s47
	s_cselect_b32 s66, s30, s46
	s_ashr_i32 s17, s16, 31
	s_lshl_b64 s[36:37], s[16:17], 19
	s_add_u32 s36, s52, s36
	s_addc_u32 s37, s53, s37
	s_and_b64 s[50:51], s[8:9], exec
	s_cselect_b32 s17, s37, s49
	s_cselect_b32 s67, s36, s48
	s_cbranch_scc1 .Lnx_11
	s_add_u32 s66, s66, 0x700
	s_addc_u32 s19, s19, 0
	s_add_u32 s67, s67, 0x700
	s_addc_u32 s17, s17, 0
.Lnx_11:
	s_add_u32 s46, s46, 0x40080
	s_addc_u32 s47, s47, 0
	s_add_u32 s68, s48, 0x100
	s_addc_u32 s69, s49, 0
	s_mov_b32 s70, -2
	ds_read_b128 v[140:143], v147
	ds_read_b128 v[150:153], v147 offset:1024
	ds_read_b128 v[154:157], v147 offset:2048
	ds_read_b128 v[158:161], v147 offset:3072
	ds_read_b128 v[162:165], v148
	ds_read_b128 v[166:169], v148 offset:1024
	ds_read_b128 v[170:173], v148 offset:2048
	ds_read_b128 v[174:177], v148 offset:3072
	s_add_u32 s48, s46, 0xfffc0080
	s_addc_u32 s49, s47, -1
	s_cmp_eq_u32 s70, 12
	s_cselect_b32 s51, s19, s49
	s_cselect_b32 s50, s66, s48
	s_cselect_b32 s49, s17, s69
	s_cselect_b32 s48, s67, s68
	v_lshl_add_u64 v[178:179], s[46:47], 0, v[132:133]
	s_add_i32 m0, s45, 0xc000
	ds_read_b128 v[184:187], v149
	ds_read_b128 v[188:191], v149 offset:1024
	ds_read_b128 v[192:195], v149 offset:2048
	ds_read_b128 v[196:199], v149 offset:3072
	ds_read_b128 v[200:203], v149 offset:4096
	ds_read_b128 v[204:207], v149 offset:5120
	ds_read_b128 v[208:211], v149 offset:6144
	ds_read_b128 v[212:215], v149 offset:7168
	global_load_lds_dwordx4 v[178:179], off
	v_lshl_add_u64 v[178:179], s[46:47], 0, v[134:135]
	s_add_i32 m0, s45, 0xe000
	s_nop 0
	global_load_lds_dwordx4 v[178:179], off
	s_waitcnt vmcnt(8)
	s_waitcnt lgkmcnt(0)
	s_barrier
	s_setprio 1
	s_waitcnt lgkmcnt(0)
	v_mfma_f32_16x16x32_bf16 v[124:127], v[140:143], v[184:187], 0
	v_mfma_f32_16x16x32_bf16 v[124:127], v[150:153], v[188:191], v[124:127]
	v_mfma_f32_16x16x32_bf16 v[120:123], v[154:157], v[184:187], 0
	v_mfma_f32_16x16x32_bf16 v[120:123], v[158:161], v[188:191], v[120:123]
	v_mfma_f32_16x16x32_bf16 v[108:111], v[140:143], v[192:195], 0
	v_mfma_f32_16x16x32_bf16 v[108:111], v[150:153], v[196:199], v[108:111]
	v_mfma_f32_16x16x32_bf16 v[104:107], v[154:157], v[192:195], 0
	v_mfma_f32_16x16x32_bf16 v[104:107], v[158:161], v[196:199], v[104:107]
	v_mfma_f32_16x16x32_bf16 v[92:95], v[140:143], v[200:203], 0
	v_mfma_f32_16x16x32_bf16 v[92:95], v[150:153], v[204:207], v[92:95]
	v_mfma_f32_16x16x32_bf16 v[88:91], v[154:157], v[200:203], 0
	v_mfma_f32_16x16x32_bf16 v[88:91], v[158:161], v[204:207], v[88:91]
	v_mfma_f32_16x16x32_bf16 v[76:79], v[140:143], v[208:211], 0
	v_mfma_f32_16x16x32_bf16 v[76:79], v[150:153], v[212:215], v[76:79]
	v_mfma_f32_16x16x32_bf16 v[72:75], v[154:157], v[208:211], 0
	v_mfma_f32_16x16x32_bf16 v[72:75], v[158:161], v[212:215], v[72:75]
	v_mfma_f32_16x16x32_bf16 v[116:119], v[162:165], v[184:187], 0
	v_mfma_f32_16x16x32_bf16 v[116:119], v[166:169], v[188:191], v[116:119]
	v_mfma_f32_16x16x32_bf16 v[112:115], v[170:173], v[184:187], 0
	v_mfma_f32_16x16x32_bf16 v[112:115], v[174:177], v[188:191], v[112:115]
	v_mfma_f32_16x16x32_bf16 v[100:103], v[162:165], v[192:195], 0
	v_mfma_f32_16x16x32_bf16 v[100:103], v[166:169], v[196:199], v[100:103]
	v_mfma_f32_16x16x32_bf16 v[96:99], v[170:173], v[192:195], 0
	v_mfma_f32_16x16x32_bf16 v[96:99], v[174:177], v[196:199], v[96:99]
	v_mfma_f32_16x16x32_bf16 v[84:87], v[162:165], v[200:203], 0
	v_mfma_f32_16x16x32_bf16 v[84:87], v[166:169], v[204:207], v[84:87]
	v_mfma_f32_16x16x32_bf16 v[80:83], v[170:173], v[200:203], 0
	v_mfma_f32_16x16x32_bf16 v[80:83], v[174:177], v[204:207], v[80:83]
	v_mfma_f32_16x16x32_bf16 v[68:71], v[162:165], v[208:211], 0
	v_mfma_f32_16x16x32_bf16 v[68:71], v[166:169], v[212:215], v[68:71]
	v_mfma_f32_16x16x32_bf16 v[64:67], v[170:173], v[208:211], 0
	v_mfma_f32_16x16x32_bf16 v[64:67], v[174:177], v[212:215], v[64:67]
	s_setprio 0
	s_barrier
	s_add_i32 s71, s62, s54
	v_lshl_add_u64 v[178:179], s[48:49], 0, v[130:131]
	s_mov_b32 m0, s71
	ds_read_b128 v[184:187], v149 offset:16384
	ds_read_b128 v[188:191], v149 offset:17408
	ds_read_b128 v[192:195], v149 offset:18432
	ds_read_b128 v[196:199], v149 offset:19456
	ds_read_b128 v[200:203], v149 offset:20480
	ds_read_b128 v[204:207], v149 offset:21504
	ds_read_b128 v[208:211], v149 offset:22528
	ds_read_b128 v[212:215], v149 offset:23552
	global_load_lds_dwordx4 v[178:179], off
	s_add_i32 m0, s71, 0x2000
	s_add_u32 s72, s48, 0x40000
	v_lshl_add_u64 v[216:217], s[48:49], 0, v[128:129]
	s_addc_u32 s73, s49, 0
	s_add_i32 s71, s63, s54
	global_load_lds_dwordx4 v[216:217], off
	v_lshl_add_u64 v[218:219], s[72:73], 0, v[130:131]
	s_mov_b32 m0, s71
	v_lshl_add_u64 v[220:221], s[50:51], 0, v[128:129]
	global_load_lds_dwordx4 v[218:219], off
	v_lshl_add_u64 v[218:219], s[72:73], 0, v[128:129]
	s_add_i32 m0, s71, 0x2000
	s_nop 0
	global_load_lds_dwordx4 v[218:219], off
	v_lshl_add_u64 v[218:219], s[50:51], 0, v[130:131]
	s_mov_b32 m0, s45
	s_nop 0
	global_load_lds_dwordx4 v[218:219], off
	s_mov_b32 m0, s56
	s_nop 0
	global_load_lds_dwordx4 v[220:221], off
	s_waitcnt vmcnt(8)
	s_waitcnt lgkmcnt(0)
	s_barrier
	s_setprio 1
	s_waitcnt lgkmcnt(0)
	v_mfma_f32_16x16x32_bf16 v[60:63], v[140:143], v[184:187], 0
	v_mfma_f32_16x16x32_bf16 v[60:63], v[150:153], v[188:191], v[60:63]
	v_mfma_f32_16x16x32_bf16 v[56:59], v[154:157], v[184:187], 0
	v_mfma_f32_16x16x32_bf16 v[56:59], v[158:161], v[188:191], v[56:59]
	v_mfma_f32_16x16x32_bf16 v[44:47], v[140:143], v[192:195], 0
	v_mfma_f32_16x16x32_bf16 v[44:47], v[150:153], v[196:199], v[44:47]
	v_mfma_f32_16x16x32_bf16 v[40:43], v[154:157], v[192:195], 0
	v_mfma_f32_16x16x32_bf16 v[40:43], v[158:161], v[196:199], v[40:43]
	v_mfma_f32_16x16x32_bf16 v[28:31], v[140:143], v[200:203], 0
	v_mfma_f32_16x16x32_bf16 v[28:31], v[150:153], v[204:207], v[28:31]
	v_mfma_f32_16x16x32_bf16 v[24:27], v[154:157], v[200:203], 0
	v_mfma_f32_16x16x32_bf16 v[24:27], v[158:161], v[204:207], v[24:27]
	v_mfma_f32_16x16x32_bf16 v[12:15], v[140:143], v[208:211], 0
	v_mfma_f32_16x16x32_bf16 v[12:15], v[150:153], v[212:215], v[12:15]
	v_mfma_f32_16x16x32_bf16 v[8:11], v[154:157], v[208:211], 0
	v_mfma_f32_16x16x32_bf16 v[8:11], v[158:161], v[212:215], v[8:11]
	v_mfma_f32_16x16x32_bf16 v[52:55], v[162:165], v[184:187], 0
	v_mfma_f32_16x16x32_bf16 v[52:55], v[166:169], v[188:191], v[52:55]
	v_mfma_f32_16x16x32_bf16 v[48:51], v[170:173], v[184:187], 0
	v_mfma_f32_16x16x32_bf16 v[48:51], v[174:177], v[188:191], v[48:51]
	v_mfma_f32_16x16x32_bf16 v[36:39], v[162:165], v[192:195], 0
	v_mfma_f32_16x16x32_bf16 v[36:39], v[166:169], v[196:199], v[36:39]
	v_mfma_f32_16x16x32_bf16 v[32:35], v[170:173], v[192:195], 0
	v_mfma_f32_16x16x32_bf16 v[32:35], v[174:177], v[196:199], v[32:35]
	v_mfma_f32_16x16x32_bf16 v[20:23], v[162:165], v[200:203], 0
	v_mfma_f32_16x16x32_bf16 v[20:23], v[166:169], v[204:207], v[20:23]
	v_mfma_f32_16x16x32_bf16 v[16:19], v[170:173], v[200:203], 0
	v_mfma_f32_16x16x32_bf16 v[16:19], v[174:177], v[204:207], v[16:19]
	v_mfma_f32_16x16x32_bf16 v[4:7], v[162:165], v[208:211], 0
	v_mfma_f32_16x16x32_bf16 v[4:7], v[166:169], v[212:215], v[4:7]
	v_mfma_f32_16x16x32_bf16 v[0:3], v[170:173], v[208:211], 0
	v_mfma_f32_16x16x32_bf16 v[0:3], v[174:177], v[212:215], v[0:3]
	s_setprio 0
	s_barrier
	s_branch .Lmid_gemm11

.LBB0_1513:
	s_cbranch_vccz .Lnx_12
	s_add_u32 s8, s8, 0x1500
	s_addc_u32 s9, s9, 0
	s_add_u32 s44, s44, 0x1500
	s_addc_u32 s45, s45, 0
